# EpiBf (xq, ffn1) epilogues de-serialized: SS loads batched + permlane row sums, on top of hand-written in-proj epilogue and hgrn pass2
# speedup vs baseline: 1.0407x; 1.0113x over previous
.LBB0_40:
	v_readlane_b32 s4, v250, 25
	v_mbcnt_lo_u32_b32 v147, -1, 0
	v_mbcnt_hi_u32_b32 v147, -1, v147
	s_nop 1
	s_lshr_b32 s5, s4, 8
	s_bfe_u32 s4, s4, 0x20006
	v_and_b32_e32 v148, 15, v147
	v_lshrrev_b32_e32 v149, 4, v147
	s_lshl_b32 s70, s28, 8
	s_lshl_b32 s5, s5, 6
	s_add_u32 s5, s5, s70
	v_add_u32_e32 v148, s5, v148
	v_lshlrev_b32_e32 v139, 6, v148
	v_lshl_add_u32 v139, v149, 4, v139
	v_lshlrev_b32_e32 v138, 13, v148
	v_lshl_add_u32 v138, v149, 4, v138
	s_lshl_b32 s4, s4, 6
	v_add_u32_e32 v138, s4, v138
	s_lshl_b32 s70, s25, 9
	s_add_u32 s54, s80, s70
	s_addc_u32 s55, s81, 0
	v_readlane_b32 s74, v250, 26
	v_readlane_b32 s75, v250, 27
	s_nop 4
	global_load_dwordx4 v[154:157], v139, s[74:75]
	global_load_dwordx4 v[158:161], v139, s[74:75] offset:1024
	global_load_dwordx4 v[162:165], v139, s[74:75] offset:2048
	global_load_dwordx4 v[166:169], v139, s[74:75] offset:3072
	v_add_u32_e32 v139, 0x2000, v139
	s_waitcnt vmcnt(0)
	v_add_f32_e32 v154, v154, v155
	v_add_f32_e32 v156, v156, v157
	v_add_f32_e32 v147, v154, v156
	v_add_f32_e32 v158, v158, v159
	v_add_f32_e32 v160, v160, v161
	v_add_f32_e32 v148, v158, v160
	v_add_f32_e32 v162, v162, v163
	v_add_f32_e32 v164, v164, v165
	v_add_f32_e32 v149, v162, v164
	v_add_f32_e32 v166, v166, v167
	v_add_f32_e32 v168, v168, v169
	v_add_f32_e32 v171, v166, v168
	global_load_dwordx4 v[154:157], v139, s[74:75]
	global_load_dwordx4 v[158:161], v139, s[74:75] offset:1024
	global_load_dwordx4 v[162:165], v139, s[74:75] offset:2048
	global_load_dwordx4 v[166:169], v139, s[74:75] offset:3072
	v_mov_b32_e32 v170, v147
	s_nop 1
	v_permlane16_swap_b32_e32 v170, v147
	v_add_f32_e32 v147, v170, v147
	v_mov_b32_e32 v170, v148
	s_nop 1
	v_permlane16_swap_b32_e32 v170, v148
	v_add_f32_e32 v148, v170, v148
	v_mov_b32_e32 v170, v149
	s_nop 1
	v_permlane16_swap_b32_e32 v170, v149
	v_add_f32_e32 v149, v170, v149
	v_mov_b32_e32 v170, v171
	s_nop 1
	v_permlane16_swap_b32_e32 v170, v171
	v_add_f32_e32 v171, v170, v171
	v_mov_b32_e32 v170, v147
	s_nop 1
	v_permlane32_swap_b32_e32 v170, v147
	v_add_f32_e32 v147, v170, v147
	v_mov_b32_e32 v170, v148
	s_nop 1
	v_permlane32_swap_b32_e32 v170, v148
	v_add_f32_e32 v148, v170, v148
	v_mov_b32_e32 v170, v149
	s_nop 1
	v_permlane32_swap_b32_e32 v170, v149
	v_add_f32_e32 v149, v170, v149
	v_mov_b32_e32 v170, v171
	s_nop 1
	v_permlane32_swap_b32_e32 v170, v171
	v_add_f32_e32 v171, v170, v171
	v_fmamk_f32 v147, v147, 0x3a800000, v176
	v_fmamk_f32 v148, v148, 0x3a800000, v176
	v_fmamk_f32 v149, v149, 0x3a800000, v176
	v_fmamk_f32 v171, v171, 0x3a800000, v176
	v_rsq_f32_e32 v147, v147
	v_rsq_f32_e32 v148, v148
	v_rsq_f32_e32 v149, v149
	v_rsq_f32_e32 v171, v171
	s_nop 0
	v_mul_f32_e32 v147, v147, v147
	v_mul_f32_e32 v148, v148, v148
	v_mul_f32_e32 v149, v149, v149
	v_mul_f32_e32 v171, v171, v171
	s_waitcnt vmcnt(0)
	v_add_f32_e32 v154, v154, v155
	v_add_f32_e32 v156, v156, v157
	v_add_f32_e32 v154, v154, v156
	v_add_f32_e32 v158, v158, v159
	v_add_f32_e32 v160, v160, v161
	v_add_f32_e32 v158, v158, v160
	v_add_f32_e32 v162, v162, v163
	v_add_f32_e32 v164, v164, v165
	v_add_f32_e32 v162, v162, v164
	v_add_f32_e32 v166, v166, v167
	v_add_f32_e32 v168, v168, v169
	v_add_f32_e32 v166, v166, v168
	v_mov_b32_e32 v170, v154
	s_nop 1
	v_permlane16_swap_b32_e32 v170, v154
	v_add_f32_e32 v154, v170, v154
	v_mov_b32_e32 v170, v158
	s_nop 1
	v_permlane16_swap_b32_e32 v170, v158
	v_add_f32_e32 v158, v170, v158
	v_mov_b32_e32 v170, v162
	s_nop 1
	v_permlane16_swap_b32_e32 v170, v162
	v_add_f32_e32 v162, v170, v162
	v_mov_b32_e32 v170, v166
	s_nop 1
	v_permlane16_swap_b32_e32 v170, v166
	v_add_f32_e32 v166, v170, v166
	v_mov_b32_e32 v170, v154
	s_nop 1
	v_permlane32_swap_b32_e32 v170, v154
	v_add_f32_e32 v154, v170, v154
	v_mov_b32_e32 v170, v158
	s_nop 1
	v_permlane32_swap_b32_e32 v170, v158
	v_add_f32_e32 v158, v170, v158
	v_mov_b32_e32 v170, v162
	s_nop 1
	v_permlane32_swap_b32_e32 v170, v162
	v_add_f32_e32 v162, v170, v162
	v_mov_b32_e32 v170, v166
	s_nop 1
	v_permlane32_swap_b32_e32 v170, v166
	v_add_f32_e32 v166, v170, v166
	v_fmamk_f32 v154, v154, 0x3a800000, v176
	v_fmamk_f32 v158, v158, 0x3a800000, v176
	v_fmamk_f32 v162, v162, 0x3a800000, v176
	v_fmamk_f32 v166, v166, 0x3a800000, v176
	v_rsq_f32_e32 v154, v154
	v_rsq_f32_e32 v158, v158
	v_rsq_f32_e32 v162, v162
	v_rsq_f32_e32 v166, v166
	s_nop 0
	v_mul_f32_e32 v154, v154, v154
	v_mul_f32_e32 v158, v158, v158
	v_mul_f32_e32 v162, v162, v162
	v_mul_f32_e32 v166, v166, v166
	v_max_f32_e32 v126, 0, v126
	v_max_f32_e32 v127, 0, v127
	v_max_f32_e32 v128, 0, v128
	v_max_f32_e32 v129, 0, v129
	v_max_f32_e32 v122, 0, v122
	v_max_f32_e32 v123, 0, v123
	v_max_f32_e32 v124, 0, v124
	v_max_f32_e32 v125, 0, v125
	v_pk_mul_f32 v[126:127], v[126:127], v[126:127]
	v_pk_mul_f32 v[128:129], v[128:129], v[128:129]
	v_pk_mul_f32 v[122:123], v[122:123], v[122:123]
	v_pk_mul_f32 v[124:125], v[124:125], v[124:125]
	v_mul_f32_e32 v126, v126, v147
	v_mul_f32_e32 v127, v127, v147
	v_mul_f32_e32 v128, v128, v147
	v_mul_f32_e32 v129, v129, v147
	v_mul_f32_e32 v122, v122, v147
	v_mul_f32_e32 v123, v123, v147
	v_mul_f32_e32 v124, v124, v147
	v_mul_f32_e32 v125, v125, v147
	v_cvt_pk_bf16_f32 v126, v126, v127
	v_cvt_pk_bf16_f32 v127, v128, v129
	v_cvt_pk_bf16_f32 v128, v122, v123
	v_cvt_pk_bf16_f32 v129, v124, v125
	global_store_dwordx4 v138, v[126:129], s[54:55]
	v_max_f32_e32 v118, 0, v118
	v_max_f32_e32 v119, 0, v119
	v_max_f32_e32 v120, 0, v120
	v_max_f32_e32 v121, 0, v121
	v_max_f32_e32 v114, 0, v114
	v_max_f32_e32 v115, 0, v115
	v_max_f32_e32 v116, 0, v116
	v_max_f32_e32 v117, 0, v117
	v_pk_mul_f32 v[118:119], v[118:119], v[118:119]
	v_pk_mul_f32 v[120:121], v[120:121], v[120:121]
	v_pk_mul_f32 v[114:115], v[114:115], v[114:115]
	v_pk_mul_f32 v[116:117], v[116:117], v[116:117]
	v_mul_f32_e32 v118, v118, v147
	v_mul_f32_e32 v119, v119, v147
	v_mul_f32_e32 v120, v120, v147
	v_mul_f32_e32 v121, v121, v147
	v_mul_f32_e32 v114, v114, v147
	v_mul_f32_e32 v115, v115, v147
	v_mul_f32_e32 v116, v116, v147
	v_mul_f32_e32 v117, v117, v147
	v_cvt_pk_bf16_f32 v118, v118, v119
	v_cvt_pk_bf16_f32 v119, v120, v121
	v_cvt_pk_bf16_f32 v120, v114, v115
	v_cvt_pk_bf16_f32 v121, v116, v117
	global_store_dwordx4 v138, v[118:121], s[54:55] offset:256
	v_add_u32_e32 v138, 0x20000, v138
	v_max_f32_e32 v110, 0, v110
	v_max_f32_e32 v111, 0, v111
	v_max_f32_e32 v112, 0, v112
	v_max_f32_e32 v113, 0, v113
	v_max_f32_e32 v106, 0, v106
	v_max_f32_e32 v107, 0, v107
	v_max_f32_e32 v108, 0, v108
	v_max_f32_e32 v109, 0, v109
	v_pk_mul_f32 v[110:111], v[110:111], v[110:111]
	v_pk_mul_f32 v[112:113], v[112:113], v[112:113]
	v_pk_mul_f32 v[106:107], v[106:107], v[106:107]
	v_pk_mul_f32 v[108:109], v[108:109], v[108:109]
	v_mul_f32_e32 v110, v110, v148
	v_mul_f32_e32 v111, v111, v148
	v_mul_f32_e32 v112, v112, v148
	v_mul_f32_e32 v113, v113, v148
	v_mul_f32_e32 v106, v106, v148
	v_mul_f32_e32 v107, v107, v148
	v_mul_f32_e32 v108, v108, v148
	v_mul_f32_e32 v109, v109, v148
	v_cvt_pk_bf16_f32 v110, v110, v111
	v_cvt_pk_bf16_f32 v111, v112, v113
	v_cvt_pk_bf16_f32 v112, v106, v107
	v_cvt_pk_bf16_f32 v113, v108, v109
	global_store_dwordx4 v138, v[110:113], s[54:55]
	v_max_f32_e32 v102, 0, v102
	v_max_f32_e32 v103, 0, v103
	v_max_f32_e32 v104, 0, v104
	v_max_f32_e32 v105, 0, v105
	v_max_f32_e32 v98, 0, v98
	v_max_f32_e32 v99, 0, v99
	v_max_f32_e32 v100, 0, v100
	v_max_f32_e32 v101, 0, v101
	v_pk_mul_f32 v[102:103], v[102:103], v[102:103]
	v_pk_mul_f32 v[104:105], v[104:105], v[104:105]
	v_pk_mul_f32 v[98:99], v[98:99], v[98:99]
	v_pk_mul_f32 v[100:101], v[100:101], v[100:101]
	v_mul_f32_e32 v102, v102, v148
	v_mul_f32_e32 v103, v103, v148
	v_mul_f32_e32 v104, v104, v148
	v_mul_f32_e32 v105, v105, v148
	v_mul_f32_e32 v98, v98, v148
	v_mul_f32_e32 v99, v99, v148
	v_mul_f32_e32 v100, v100, v148
	v_mul_f32_e32 v101, v101, v148
	v_cvt_pk_bf16_f32 v102, v102, v103
	v_cvt_pk_bf16_f32 v103, v104, v105
	v_cvt_pk_bf16_f32 v104, v98, v99
	v_cvt_pk_bf16_f32 v105, v100, v101
	global_store_dwordx4 v138, v[102:105], s[54:55] offset:256
	v_add_u32_e32 v138, 0x20000, v138
	v_max_f32_e32 v94, 0, v94
	v_max_f32_e32 v95, 0, v95
	v_max_f32_e32 v96, 0, v96
	v_max_f32_e32 v97, 0, v97
	v_max_f32_e32 v90, 0, v90
	v_max_f32_e32 v91, 0, v91
	v_max_f32_e32 v92, 0, v92
	v_max_f32_e32 v93, 0, v93
	v_pk_mul_f32 v[94:95], v[94:95], v[94:95]
	v_pk_mul_f32 v[96:97], v[96:97], v[96:97]
	v_pk_mul_f32 v[90:91], v[90:91], v[90:91]
	v_pk_mul_f32 v[92:93], v[92:93], v[92:93]
	v_mul_f32_e32 v94, v94, v149
	v_mul_f32_e32 v95, v95, v149
	v_mul_f32_e32 v96, v96, v149
	v_mul_f32_e32 v97, v97, v149
	v_mul_f32_e32 v90, v90, v149
	v_mul_f32_e32 v91, v91, v149
	v_mul_f32_e32 v92, v92, v149
	v_mul_f32_e32 v93, v93, v149
	v_cvt_pk_bf16_f32 v94, v94, v95
	v_cvt_pk_bf16_f32 v95, v96, v97
	v_cvt_pk_bf16_f32 v96, v90, v91
	v_cvt_pk_bf16_f32 v97, v92, v93
	global_store_dwordx4 v138, v[94:97], s[54:55]
	v_max_f32_e32 v86, 0, v86
	v_max_f32_e32 v87, 0, v87
	v_max_f32_e32 v88, 0, v88
	v_max_f32_e32 v89, 0, v89
	v_max_f32_e32 v82, 0, v82
	v_max_f32_e32 v83, 0, v83
	v_max_f32_e32 v84, 0, v84
	v_max_f32_e32 v85, 0, v85
	v_pk_mul_f32 v[86:87], v[86:87], v[86:87]
	v_pk_mul_f32 v[88:89], v[88:89], v[88:89]
	v_pk_mul_f32 v[82:83], v[82:83], v[82:83]
	v_pk_mul_f32 v[84:85], v[84:85], v[84:85]
	v_mul_f32_e32 v86, v86, v149
	v_mul_f32_e32 v87, v87, v149
	v_mul_f32_e32 v88, v88, v149
	v_mul_f32_e32 v89, v89, v149
	v_mul_f32_e32 v82, v82, v149
	v_mul_f32_e32 v83, v83, v149
	v_mul_f32_e32 v84, v84, v149
	v_mul_f32_e32 v85, v85, v149
	v_cvt_pk_bf16_f32 v86, v86, v87
	v_cvt_pk_bf16_f32 v87, v88, v89
	v_cvt_pk_bf16_f32 v88, v82, v83
	v_cvt_pk_bf16_f32 v89, v84, v85
	global_store_dwordx4 v138, v[86:89], s[54:55] offset:256
	v_add_u32_e32 v138, 0x20000, v138
	v_max_f32_e32 v78, 0, v78
	v_max_f32_e32 v79, 0, v79
	v_max_f32_e32 v80, 0, v80
	v_max_f32_e32 v81, 0, v81
	v_max_f32_e32 v74, 0, v74
	v_max_f32_e32 v75, 0, v75
	v_max_f32_e32 v76, 0, v76
	v_max_f32_e32 v77, 0, v77
	v_pk_mul_f32 v[78:79], v[78:79], v[78:79]
	v_pk_mul_f32 v[80:81], v[80:81], v[80:81]
	v_pk_mul_f32 v[74:75], v[74:75], v[74:75]
	v_pk_mul_f32 v[76:77], v[76:77], v[76:77]
	v_mul_f32_e32 v78, v78, v171
	v_mul_f32_e32 v79, v79, v171
	v_mul_f32_e32 v80, v80, v171
	v_mul_f32_e32 v81, v81, v171
	v_mul_f32_e32 v74, v74, v171
	v_mul_f32_e32 v75, v75, v171
	v_mul_f32_e32 v76, v76, v171
	v_mul_f32_e32 v77, v77, v171
	v_cvt_pk_bf16_f32 v78, v78, v79
	v_cvt_pk_bf16_f32 v79, v80, v81
	v_cvt_pk_bf16_f32 v80, v74, v75
	v_cvt_pk_bf16_f32 v81, v76, v77
	global_store_dwordx4 v138, v[78:81], s[54:55]
	v_max_f32_e32 v70, 0, v70
	v_max_f32_e32 v71, 0, v71
	v_max_f32_e32 v72, 0, v72
	v_max_f32_e32 v73, 0, v73
	v_max_f32_e32 v66, 0, v66
	v_max_f32_e32 v67, 0, v67
	v_max_f32_e32 v68, 0, v68
	v_max_f32_e32 v69, 0, v69
	v_pk_mul_f32 v[70:71], v[70:71], v[70:71]
	v_pk_mul_f32 v[72:73], v[72:73], v[72:73]
	v_pk_mul_f32 v[66:67], v[66:67], v[66:67]
	v_pk_mul_f32 v[68:69], v[68:69], v[68:69]
	v_mul_f32_e32 v70, v70, v171
	v_mul_f32_e32 v71, v71, v171
	v_mul_f32_e32 v72, v72, v171
	v_mul_f32_e32 v73, v73, v171
	v_mul_f32_e32 v66, v66, v171
	v_mul_f32_e32 v67, v67, v171
	v_mul_f32_e32 v68, v68, v171
	v_mul_f32_e32 v69, v69, v171
	v_cvt_pk_bf16_f32 v70, v70, v71
	v_cvt_pk_bf16_f32 v71, v72, v73
	v_cvt_pk_bf16_f32 v72, v66, v67
	v_cvt_pk_bf16_f32 v73, v68, v69
	global_store_dwordx4 v138, v[70:73], s[54:55] offset:256
	v_add_u32_e32 v138, 0xa0000, v138
	v_max_f32_e32 v60, 0, v60
	v_max_f32_e32 v61, 0, v61
	v_max_f32_e32 v62, 0, v62
	v_max_f32_e32 v63, 0, v63
	v_max_f32_e32 v56, 0, v56
	v_max_f32_e32 v57, 0, v57
	v_max_f32_e32 v58, 0, v58
	v_max_f32_e32 v59, 0, v59
	v_pk_mul_f32 v[60:61], v[60:61], v[60:61]
	v_pk_mul_f32 v[62:63], v[62:63], v[62:63]
	v_pk_mul_f32 v[56:57], v[56:57], v[56:57]
	v_pk_mul_f32 v[58:59], v[58:59], v[58:59]
	v_mul_f32_e32 v60, v60, v154
	v_mul_f32_e32 v61, v61, v154
	v_mul_f32_e32 v62, v62, v154
	v_mul_f32_e32 v63, v63, v154
	v_mul_f32_e32 v56, v56, v154
	v_mul_f32_e32 v57, v57, v154
	v_mul_f32_e32 v58, v58, v154
	v_mul_f32_e32 v59, v59, v154
	v_cvt_pk_bf16_f32 v60, v60, v61
	v_cvt_pk_bf16_f32 v61, v62, v63
	v_cvt_pk_bf16_f32 v62, v56, v57
	v_cvt_pk_bf16_f32 v63, v58, v59
	global_store_dwordx4 v138, v[60:63], s[54:55]
	v_max_f32_e32 v52, 0, v52
	v_max_f32_e32 v53, 0, v53
	v_max_f32_e32 v54, 0, v54
	v_max_f32_e32 v55, 0, v55
	v_max_f32_e32 v48, 0, v48
	v_max_f32_e32 v49, 0, v49
	v_max_f32_e32 v50, 0, v50
	v_max_f32_e32 v51, 0, v51
	v_pk_mul_f32 v[52:53], v[52:53], v[52:53]
	v_pk_mul_f32 v[54:55], v[54:55], v[54:55]
	v_pk_mul_f32 v[48:49], v[48:49], v[48:49]
	v_pk_mul_f32 v[50:51], v[50:51], v[50:51]
	v_mul_f32_e32 v52, v52, v154
	v_mul_f32_e32 v53, v53, v154
	v_mul_f32_e32 v54, v54, v154
	v_mul_f32_e32 v55, v55, v154
	v_mul_f32_e32 v48, v48, v154
	v_mul_f32_e32 v49, v49, v154
	v_mul_f32_e32 v50, v50, v154
	v_mul_f32_e32 v51, v51, v154
	v_cvt_pk_bf16_f32 v52, v52, v53
	v_cvt_pk_bf16_f32 v53, v54, v55
	v_cvt_pk_bf16_f32 v54, v48, v49
	v_cvt_pk_bf16_f32 v55, v50, v51
	global_store_dwordx4 v138, v[52:55], s[54:55] offset:256
	v_add_u32_e32 v138, 0x20000, v138
	v_max_f32_e32 v44, 0, v44
	v_max_f32_e32 v45, 0, v45
	v_max_f32_e32 v46, 0, v46
	v_max_f32_e32 v47, 0, v47
	v_max_f32_e32 v40, 0, v40
	v_max_f32_e32 v41, 0, v41
	v_max_f32_e32 v42, 0, v42
	v_max_f32_e32 v43, 0, v43
	v_pk_mul_f32 v[44:45], v[44:45], v[44:45]
	v_pk_mul_f32 v[46:47], v[46:47], v[46:47]
	v_pk_mul_f32 v[40:41], v[40:41], v[40:41]
	v_pk_mul_f32 v[42:43], v[42:43], v[42:43]
	v_mul_f32_e32 v44, v44, v158
	v_mul_f32_e32 v45, v45, v158
	v_mul_f32_e32 v46, v46, v158
	v_mul_f32_e32 v47, v47, v158
	v_mul_f32_e32 v40, v40, v158
	v_mul_f32_e32 v41, v41, v158
	v_mul_f32_e32 v42, v42, v158
	v_mul_f32_e32 v43, v43, v158
	v_cvt_pk_bf16_f32 v44, v44, v45
	v_cvt_pk_bf16_f32 v45, v46, v47
	v_cvt_pk_bf16_f32 v46, v40, v41
	v_cvt_pk_bf16_f32 v47, v42, v43
	global_store_dwordx4 v138, v[44:47], s[54:55]
	v_max_f32_e32 v36, 0, v36
	v_max_f32_e32 v37, 0, v37
	v_max_f32_e32 v38, 0, v38
	v_max_f32_e32 v39, 0, v39
	v_max_f32_e32 v32, 0, v32
	v_max_f32_e32 v33, 0, v33
	v_max_f32_e32 v34, 0, v34
	v_max_f32_e32 v35, 0, v35
	v_pk_mul_f32 v[36:37], v[36:37], v[36:37]
	v_pk_mul_f32 v[38:39], v[38:39], v[38:39]
	v_pk_mul_f32 v[32:33], v[32:33], v[32:33]
	v_pk_mul_f32 v[34:35], v[34:35], v[34:35]
	v_mul_f32_e32 v36, v36, v158
	v_mul_f32_e32 v37, v37, v158
	v_mul_f32_e32 v38, v38, v158
	v_mul_f32_e32 v39, v39, v158
	v_mul_f32_e32 v32, v32, v158
	v_mul_f32_e32 v33, v33, v158
	v_mul_f32_e32 v34, v34, v158
	v_mul_f32_e32 v35, v35, v158
	v_cvt_pk_bf16_f32 v36, v36, v37
	v_cvt_pk_bf16_f32 v37, v38, v39
	v_cvt_pk_bf16_f32 v38, v32, v33
	v_cvt_pk_bf16_f32 v39, v34, v35
	global_store_dwordx4 v138, v[36:39], s[54:55] offset:256
	v_add_u32_e32 v138, 0x20000, v138
	v_max_f32_e32 v28, 0, v28
	v_max_f32_e32 v29, 0, v29
	v_max_f32_e32 v30, 0, v30
	v_max_f32_e32 v31, 0, v31
	v_max_f32_e32 v24, 0, v24
	v_max_f32_e32 v25, 0, v25
	v_max_f32_e32 v26, 0, v26
	v_max_f32_e32 v27, 0, v27
	v_pk_mul_f32 v[28:29], v[28:29], v[28:29]
	v_pk_mul_f32 v[30:31], v[30:31], v[30:31]
	v_pk_mul_f32 v[24:25], v[24:25], v[24:25]
	v_pk_mul_f32 v[26:27], v[26:27], v[26:27]
	v_mul_f32_e32 v28, v28, v162
	v_mul_f32_e32 v29, v29, v162
	v_mul_f32_e32 v30, v30, v162
	v_mul_f32_e32 v31, v31, v162
	v_mul_f32_e32 v24, v24, v162
	v_mul_f32_e32 v25, v25, v162
	v_mul_f32_e32 v26, v26, v162
	v_mul_f32_e32 v27, v27, v162
	v_cvt_pk_bf16_f32 v28, v28, v29
	v_cvt_pk_bf16_f32 v29, v30, v31
	v_cvt_pk_bf16_f32 v30, v24, v25
	v_cvt_pk_bf16_f32 v31, v26, v27
	global_store_dwordx4 v138, v[28:31], s[54:55]
	v_max_f32_e32 v20, 0, v20
	v_max_f32_e32 v21, 0, v21
	v_max_f32_e32 v22, 0, v22
	v_max_f32_e32 v23, 0, v23
	v_max_f32_e32 v16, 0, v16
	v_max_f32_e32 v17, 0, v17
	v_max_f32_e32 v18, 0, v18
	v_max_f32_e32 v19, 0, v19
	v_pk_mul_f32 v[20:21], v[20:21], v[20:21]
	v_pk_mul_f32 v[22:23], v[22:23], v[22:23]
	v_pk_mul_f32 v[16:17], v[16:17], v[16:17]
	v_pk_mul_f32 v[18:19], v[18:19], v[18:19]
	v_mul_f32_e32 v20, v20, v162
	v_mul_f32_e32 v21, v21, v162
	v_mul_f32_e32 v22, v22, v162
	v_mul_f32_e32 v23, v23, v162
	v_mul_f32_e32 v16, v16, v162
	v_mul_f32_e32 v17, v17, v162
	v_mul_f32_e32 v18, v18, v162
	v_mul_f32_e32 v19, v19, v162
	v_cvt_pk_bf16_f32 v20, v20, v21
	v_cvt_pk_bf16_f32 v21, v22, v23
	v_cvt_pk_bf16_f32 v22, v16, v17
	v_cvt_pk_bf16_f32 v23, v18, v19
	global_store_dwordx4 v138, v[20:23], s[54:55] offset:256
	v_add_u32_e32 v138, 0x20000, v138
	v_max_f32_e32 v12, 0, v12
	v_max_f32_e32 v13, 0, v13
	v_max_f32_e32 v14, 0, v14
	v_max_f32_e32 v15, 0, v15
	v_max_f32_e32 v8, 0, v8
	v_max_f32_e32 v9, 0, v9
	v_max_f32_e32 v10, 0, v10
	v_max_f32_e32 v11, 0, v11
	v_pk_mul_f32 v[12:13], v[12:13], v[12:13]
	v_pk_mul_f32 v[14:15], v[14:15], v[14:15]
	v_pk_mul_f32 v[8:9], v[8:9], v[8:9]
	v_pk_mul_f32 v[10:11], v[10:11], v[10:11]
	v_mul_f32_e32 v12, v12, v166
	v_mul_f32_e32 v13, v13, v166
	v_mul_f32_e32 v14, v14, v166
	v_mul_f32_e32 v15, v15, v166
	v_mul_f32_e32 v8, v8, v166
	v_mul_f32_e32 v9, v9, v166
	v_mul_f32_e32 v10, v10, v166
	v_mul_f32_e32 v11, v11, v166
	v_cvt_pk_bf16_f32 v12, v12, v13
	v_cvt_pk_bf16_f32 v13, v14, v15
	v_cvt_pk_bf16_f32 v14, v8, v9
	v_cvt_pk_bf16_f32 v15, v10, v11
	global_store_dwordx4 v138, v[12:15], s[54:55]
	v_max_f32_e32 v4, 0, v4
	v_max_f32_e32 v5, 0, v5
	v_max_f32_e32 v6, 0, v6
	v_max_f32_e32 v7, 0, v7
	v_max_f32_e32 v0, 0, v0
	v_max_f32_e32 v1, 0, v1
	v_max_f32_e32 v2, 0, v2
	v_max_f32_e32 v3, 0, v3
	v_pk_mul_f32 v[4:5], v[4:5], v[4:5]
	v_pk_mul_f32 v[6:7], v[6:7], v[6:7]
	v_pk_mul_f32 v[0:1], v[0:1], v[0:1]
	v_pk_mul_f32 v[2:3], v[2:3], v[2:3]
	v_mul_f32_e32 v4, v4, v166
	v_mul_f32_e32 v5, v5, v166
	v_mul_f32_e32 v6, v6, v166
	v_mul_f32_e32 v7, v7, v166
	v_mul_f32_e32 v0, v0, v166
	v_mul_f32_e32 v1, v1, v166
	v_mul_f32_e32 v2, v2, v166
	v_mul_f32_e32 v3, v3, v166
	v_cvt_pk_bf16_f32 v4, v4, v5
	v_cvt_pk_bf16_f32 v5, v6, v7
	v_cvt_pk_bf16_f32 v6, v0, v1
	v_cvt_pk_bf16_f32 v7, v2, v3
	global_store_dwordx4 v138, v[4:7], s[54:55] offset:256
	s_andn2_b64 vcc, exec, s[38:39]
	s_mov_b64 s[4:5], -1
	s_branch .Lffn1_done
	v_lshl_add_u32 v148, s28, 8, v65
	v_ashrrev_i32_e32 v149, 31, v148
	v_readlane_b32 s28, v250, 26
	v_lshlrev_b64 v[138:139], 6, v[148:149]
	v_readlane_b32 s29, v250, 27
	v_max_f32_e32 v122, v122, v122
	v_max_f32_e32 v123, v123, v123
	v_lshl_add_u64 v[138:139], s[28:29], 0, v[138:139]
	global_load_dwordx4 v[152:155], v[138:139], off
	global_load_dwordx4 v[156:159], v[138:139], off offset:16
	global_load_dwordx4 v[160:163], v[138:139], off offset:32
	global_load_dwordx4 v[164:167], v[138:139], off offset:48
	v_max_f32_e32 v124, v124, v124
	v_max_f32_e32 v129, v129, v129
	v_max_f32_e32 v125, v125, v125
	v_max_f32_e32 v138, v114, v114
	v_max_f32_e32 v122, 0, v122
	v_max_f32_e32 v123, 0, v123
	v_max_f32_e32 v114, 0, v124
	v_max_f32_e32 v124, 0, v129
	v_max_f32_e32 v125, 0, v125
	v_mul_f32_e32 v168, v122, v122
	v_mul_f32_e32 v170, v123, v123
	v_mul_f32_e32 v172, v124, v124
	v_mul_f32_e32 v173, v125, v125
	v_max_f32_e32 v126, v126, v126
	v_max_f32_e32 v127, v127, v127
	v_max_f32_e32 v128, v128, v128
	v_max_f32_e32 v118, v118, v118
	v_max_f32_e32 v119, v119, v119
	v_max_f32_e32 v126, 0, v126
	v_max_f32_e32 v127, 0, v127
	v_max_f32_e32 v128, 0, v128
	v_max_f32_e32 v129, 0, v118
	v_max_f32_e32 v139, 0, v119
	v_lshlrev_b64 v[118:119], 13, v[148:149]
	v_mul_f32_e32 v149, v126, v126
	v_mul_f32_e32 v169, v127, v127
	v_mul_f32_e32 v171, v128, v128
	v_mul_f32_e32 v174, v129, v129
	v_max_f32_e32 v115, v115, v115
	v_max_f32_e32 v115, 0, v115
	v_mul_f32_e32 v175, v115, v115
	s_lshl_b32 s4, s25, 8
	s_ashr_i32 s5, s4, 31
	s_lshl_b64 s[54:55], s[4:5], 1
	v_lshl_add_u64 v[118:119], s[80:81], 0, v[118:119]
	v_max_f32_e32 v116, v116, v116
	v_lshl_add_u64 v[118:119], v[118:119], 0, s[54:55]
	v_mov_b32_e32 v147, v64
	v_max_f32_e32 v116, 0, v116
	v_lshl_add_u64 v[118:119], v[118:119], 0, s[76:77]
	v_mul_f32_e32 v116, v116, v116
	v_lshl_add_u64 v[118:119], v[118:119], 0, v[146:147]
	v_max_f32_e32 v120, v120, v120
	v_max_f32_e32 v138, 0, v138
	v_max_f32_e32 v120, 0, v120
	v_mul_f32_e32 v138, v138, v138
	v_mul_f32_e32 v139, v139, v139
	v_mul_f32_e32 v120, v120, v120
	v_max_f32_e32 v110, v110, v110
	v_max_f32_e32 v111, v111, v111
	v_max_f32_e32 v108, v108, v108
	v_max_f32_e32 v113, v113, v113
	v_max_f32_e32 v109, v109, v109
	v_max_f32_e32 v110, 0, v110
	v_max_f32_e32 v111, 0, v111
	v_max_f32_e32 v109, 0, v109
	v_max_f32_e32 v112, v112, v112
	v_max_f32_e32 v112, 0, v112
	v_max_f32_e32 v103, v103, v103
	v_max_f32_e32 v106, v106, v106
	v_max_f32_e32 v107, v107, v107
	v_max_f32_e32 v106, 0, v106
	v_max_f32_e32 v107, 0, v107
	v_max_f32_e32 v98, v98, v98
	v_max_f32_e32 v98, 0, v98
	v_mul_f32_e32 v98, v98, v98
	v_max_f32_e32 v100, v100, v100
	v_max_f32_e32 v100, 0, v100
	v_max_f32_e32 v94, v94, v94
	v_max_f32_e32 v95, v95, v95
	v_max_f32_e32 v96, v96, v96
	v_max_f32_e32 v90, v90, v90
	v_max_f32_e32 v92, v92, v92
	v_max_f32_e32 v97, v97, v97
	v_max_f32_e32 v94, 0, v94
	v_max_f32_e32 v95, 0, v95
	s_waitcnt vmcnt(0)
	v_mov_b32_e32 v122, v153
	v_mov_b32_e32 v123, v154
	v_mov_b32_e32 v153, v155
	v_mov_b32_e32 v124, v157
	v_mov_b32_e32 v125, v158
	v_mov_b32_e32 v157, v159
	v_pk_add_f32 v[122:123], v[122:123], v[152:153]
	v_pk_add_f32 v[124:125], v[124:125], v[156:157]
	v_pk_add_f32 v[122:123], v[122:123], v[122:123] op_sel:[0,1] op_sel_hi:[1,0]
	v_pk_add_f32 v[124:125], v[124:125], v[124:125] op_sel:[0,1] op_sel_hi:[1,0]
	v_add_f32_e32 v126, v160, v161
	v_add_f32_e32 v128, v162, v163
	v_mov_b32_e32 v127, v166
	v_mov_b32_e32 v129, v167
	v_mov_b32_e32 v123, v164
	v_mov_b32_e32 v125, v165
	v_pk_add_f32 v[126:127], v[126:127], v[128:129]
	v_pk_add_f32 v[122:123], v[122:123], v[124:125]
	v_mul_f32_e32 v152, v110, v110
	v_pk_add_f32 v[122:123], v[122:123], v[126:127]
	v_mul_f32_e32 v154, v111, v111
	v_add_f32_e32 v115, v122, v123
	v_fmamk_f32 v115, v115, 0x3a800000, v176
	v_mul_f32_e32 v122, 0x4b800000, v115
	v_cmp_gt_f32_e32 vcc, s11, v115
	v_mul_f32_e32 v158, v109, v109
	v_mul_f32_e32 v156, v112, v112
	v_cndmask_b32_e32 v115, v115, v122, vcc
	v_rsq_f32_e32 v115, v115
	v_mul_f32_e32 v153, v106, v106
	v_mul_f32_e32 v155, v107, v107
	v_max_f32_e32 v96, 0, v96
	v_mul_f32_e32 v122, 0x45800000, v115
	v_cndmask_b32_e32 v115, v115, v122, vcc
	v_pk_mul_f32 v[114:115], v[114:115], v[114:115]
	v_max_f32_e32 v91, v91, v91
	v_mul_f32_e32 v122, v149, v115
	v_mul_f32_e32 v124, v168, v115
	v_mul_f32_e32 v123, v169, v115
	v_mul_f32_e32 v125, v170, v115
	v_mul_f32_e32 v114, v114, v115
	v_mul_f32_e32 v126, v171, v115
	v_mul_f32_e32 v127, v172, v115
	v_mul_f32_e32 v128, v173, v115
	v_cvt_pk_bf16_f32 v122, v122, v123
	v_cvt_pk_bf16_f32 v123, v126, v127
	v_cvt_pk_bf16_f32 v124, v124, v125
	v_cvt_pk_bf16_f32 v125, v114, v128
	v_max_f32_e32 v114, v121, v121
	global_store_dwordx4 v[118:119], v[122:125], off
	v_max_f32_e32 v114, 0, v114
	v_mul_f32_e32 v114, v114, v114
	v_mul_f32_e32 v122, v116, v115
	v_max_f32_e32 v116, v117, v117
	v_max_f32_e32 v116, 0, v116
	v_mul_f32_e32 v138, v138, v115
	v_mul_f32_e32 v117, v114, v115
	v_mul_f32_e32 v114, v116, v116
	v_mul_f32_e32 v129, v174, v115
	v_mul_f32_e32 v139, v139, v115
	v_mul_f32_e32 v149, v175, v115
	v_mul_f32_e32 v120, v120, v115
	v_mul_f32_e32 v121, v114, v115
	v_cvt_pk_bf16_f32 v114, v129, v139
	v_cvt_pk_bf16_f32 v115, v120, v117
	v_cvt_pk_bf16_f32 v116, v138, v149
	v_or_b32_e32 v138, 16, v148
	v_ashrrev_i32_e32 v139, 31, v138
	v_cvt_pk_bf16_f32 v117, v122, v121
	global_store_dwordx4 v[118:119], v[114:117], off offset:256
	v_max_f32_e32 v149, v102, v102
	v_max_f32_e32 v102, 0, v108
	v_lshlrev_b64 v[114:115], 6, v[138:139]
	v_lshl_add_u64 v[126:127], s[28:29], 0, v[114:115]
	global_load_dwordx4 v[114:117], v[126:127], off
	global_load_dwordx4 v[118:121], v[126:127], off offset:16
	global_load_dwordx4 v[122:125], v[126:127], off offset:32
	s_nop 0
	global_load_dwordx4 v[126:129], v[126:127], off offset:48
	v_max_f32_e32 v108, 0, v113
	v_mul_f32_e32 v157, v108, v108
	v_max_f32_e32 v113, 0, v149
	v_mul_f32_e32 v159, v113, v113
	v_max_f32_e32 v149, 0, v103
	v_lshlrev_b64 v[106:107], 13, v[138:139]
	v_lshl_add_u64 v[106:107], s[80:81], 0, v[106:107]
	v_lshl_add_u64 v[106:107], v[106:107], 0, s[54:55]
	v_lshl_add_u64 v[106:107], v[106:107], 0, s[76:77]
	v_max_f32_e32 v91, 0, v91
	v_max_f32_e32 v93, v93, v93
	v_max_f32_e32 v93, 0, v93
	v_max_f32_e32 v82, v82, v82
	v_max_f32_e32 v83, v83, v83
	v_max_f32_e32 v82, 0, v82
	v_max_f32_e32 v83, 0, v83
	v_max_f32_e32 v84, v84, v84
	v_mul_f32_e32 v82, v82, v82
	v_mul_f32_e32 v83, v83, v83
	v_max_f32_e32 v84, 0, v84
	v_mul_f32_e32 v84, v84, v84
	v_max_f32_e32 v86, v86, v86
	v_max_f32_e32 v85, v85, v85
	v_max_f32_e32 v86, 0, v86
	v_max_f32_e32 v85, 0, v85
	v_mul_f32_e32 v86, v86, v86
	v_mul_f32_e32 v85, v85, v85
	v_max_f32_e32 v78, v78, v78
	v_max_f32_e32 v79, v79, v79
	v_max_f32_e32 v74, v74, v74
	v_max_f32_e32 v76, v76, v76
	v_max_f32_e32 v78, 0, v78
	v_max_f32_e32 v79, 0, v79
	v_max_f32_e32 v75, v75, v75
	v_max_f32_e32 v75, 0, v75
	v_max_f32_e32 v77, v77, v77
	v_max_f32_e32 v80, v80, v80
	v_max_f32_e32 v81, v81, v81
	v_max_f32_e32 v77, 0, v77
	v_max_f32_e32 v66, v66, v66
	v_max_f32_e32 v67, v67, v67
	v_max_f32_e32 v80, 0, v80
	v_max_f32_e32 v81, 0, v81
	v_mul_f32_e32 v77, v77, v77
	v_max_f32_e32 v66, 0, v66
	v_max_f32_e32 v67, 0, v67
	v_max_f32_e32 v68, v68, v68
	v_mul_f32_e32 v80, v80, v80
	v_mul_f32_e32 v81, v81, v81
	v_mul_f32_e32 v66, v66, v66
	v_mul_f32_e32 v67, v67, v67
	v_max_f32_e32 v68, 0, v68
	v_mul_f32_e32 v68, v68, v68
	v_max_f32_e32 v70, v70, v70
	v_max_f32_e32 v69, v69, v69
	v_max_f32_e32 v70, 0, v70
	v_max_f32_e32 v69, 0, v69
	v_mul_f32_e32 v70, v70, v70
	v_mul_f32_e32 v69, v69, v69
	v_max_f32_e32 v60, v60, v60
	v_max_f32_e32 v60, 0, v60
	v_max_f32_e32 v57, v57, v57
	v_max_f32_e32 v58, v58, v58
	v_max_f32_e32 v57, 0, v57
	v_max_f32_e32 v56, v56, v56
	v_mul_f32_e32 v57, v57, v57
	v_max_f32_e32 v56, 0, v56
	v_max_f32_e32 v59, v59, v59
	v_mul_f32_e32 v56, v56, v56
	v_max_f32_e32 v59, 0, v59
	v_max_f32_e32 v48, v48, v48
	v_max_f32_e32 v49, v49, v49
	v_max_f32_e32 v50, v50, v50
	v_mul_f32_e32 v59, v59, v59
	v_max_f32_e32 v48, 0, v48
	v_max_f32_e32 v49, 0, v49
	s_waitcnt vmcnt(3)
	v_mov_b32_e32 v108, v115
	v_mov_b32_e32 v109, v116
	v_mov_b32_e32 v115, v117
	s_waitcnt vmcnt(2)
	v_mov_b32_e32 v110, v119
	v_mov_b32_e32 v111, v120
	v_mov_b32_e32 v119, v121
	v_pk_add_f32 v[108:109], v[108:109], v[114:115]
	v_pk_add_f32 v[110:111], v[110:111], v[118:119]
	v_pk_add_f32 v[108:109], v[108:109], v[108:109] op_sel:[0,1] op_sel_hi:[1,0]
	v_pk_add_f32 v[110:111], v[110:111], v[110:111] op_sel:[0,1] op_sel_hi:[1,0]
	s_waitcnt vmcnt(1)
	v_add_f32_e32 v112, v122, v123
	v_add_f32_e32 v116, v124, v125
	s_waitcnt vmcnt(0)
	v_mov_b32_e32 v113, v128
	v_mov_b32_e32 v117, v129
	v_mov_b32_e32 v109, v126
	v_mov_b32_e32 v111, v127
	v_pk_add_f32 v[112:113], v[112:113], v[116:117]
	v_pk_add_f32 v[108:109], v[108:109], v[110:111]
	v_lshl_add_u64 v[110:111], v[106:107], 0, v[146:147]
	v_pk_add_f32 v[108:109], v[108:109], v[112:113]
	v_mul_f32_e32 v117, v94, v94
	v_add_f32_e32 v103, v108, v109
	v_fmamk_f32 v103, v103, 0x3a800000, v176
	v_mul_f32_e32 v108, 0x4b800000, v103
	v_cmp_gt_f32_e32 vcc, s11, v103
	v_mul_f32_e32 v118, v95, v95
	v_mul_f32_e32 v120, v96, v96
	v_cndmask_b32_e32 v103, v103, v108, vcc
	v_rsq_f32_e32 v103, v103
	v_mul_f32_e32 v119, v91, v91
	v_mul_f32_e32 v122, v93, v93
	v_max_f32_e32 v50, 0, v50
	v_mul_f32_e32 v106, 0x45800000, v103
	v_cndmask_b32_e32 v103, v103, v106, vcc
	v_pk_mul_f32 v[102:103], v[102:103], v[102:103]
	v_mul_f32_e32 v48, v48, v48
	v_mul_f32_e32 v116, v98, v103
	v_max_f32_e32 v98, v99, v99
	v_max_f32_e32 v98, 0, v98
	v_mul_f32_e32 v106, v152, v103
	v_mul_f32_e32 v108, v153, v103
	v_mul_f32_e32 v107, v154, v103
	v_mul_f32_e32 v109, v155, v103
	v_mul_f32_e32 v102, v102, v103
	v_mul_f32_e32 v98, v98, v98
	v_mul_f32_e32 v112, v156, v103
	v_mul_f32_e32 v113, v157, v103
	v_mul_f32_e32 v114, v158, v103
	v_cvt_pk_bf16_f32 v106, v106, v107
	v_cvt_pk_bf16_f32 v107, v112, v113
	v_cvt_pk_bf16_f32 v108, v108, v109
	v_cvt_pk_bf16_f32 v109, v102, v114
	v_mul_f32_e32 v102, v98, v103
	v_max_f32_e32 v98, v104, v104
	v_max_f32_e32 v98, 0, v98
	v_mul_f32_e32 v98, v98, v98
	v_mul_f32_e32 v104, v98, v103
	v_mul_f32_e32 v98, v100, v100
	global_store_dwordx4 v[110:111], v[106:109], off
	v_max_f32_e32 v100, v101, v101
	v_mul_f32_e32 v99, v149, v149
	v_mul_f32_e32 v106, v98, v103
	v_max_f32_e32 v98, v105, v105
	v_max_f32_e32 v98, 0, v98
	v_max_f32_e32 v100, 0, v100
	v_mul_f32_e32 v98, v98, v98
	v_mul_f32_e32 v115, v159, v103
	v_mul_f32_e32 v99, v99, v103
	v_mul_f32_e32 v101, v98, v103
	v_mul_f32_e32 v98, v100, v100
	v_or_b32_e32 v114, 32, v148
	v_mul_f32_e32 v103, v98, v103
	v_cvt_pk_bf16_f32 v98, v115, v99
	v_cvt_pk_bf16_f32 v99, v104, v101
	v_ashrrev_i32_e32 v115, 31, v114
	v_cvt_pk_bf16_f32 v100, v116, v102
	v_cvt_pk_bf16_f32 v101, v106, v103
	global_store_dwordx4 v[110:111], v[98:101], off offset:256
	v_max_f32_e32 v116, 0, v90
	v_max_f32_e32 v90, 0, v92
	v_lshlrev_b64 v[98:99], 6, v[114:115]
	v_lshl_add_u64 v[110:111], s[28:29], 0, v[98:99]
	global_load_dwordx4 v[98:101], v[110:111], off
	global_load_dwordx4 v[102:105], v[110:111], off offset:16
	global_load_dwordx4 v[106:109], v[110:111], off offset:32
	s_nop 0
	global_load_dwordx4 v[110:113], v[110:111], off offset:48
	v_max_f32_e32 v92, 0, v97
	v_mul_f32_e32 v121, v92, v92
	v_lshlrev_b64 v[92:93], 13, v[114:115]
	v_lshl_add_u64 v[92:93], s[80:81], 0, v[92:93]
	v_lshl_add_u64 v[92:93], v[92:93], 0, s[54:55]
	v_lshl_add_u64 v[92:93], v[92:93], 0, s[76:77]
	v_mul_f32_e32 v116, v116, v116
	v_mul_f32_e32 v49, v49, v49
	v_mul_f32_e32 v50, v50, v50
	v_max_f32_e32 v51, v51, v51
	v_max_f32_e32 v52, v52, v52
	v_max_f32_e32 v51, 0, v51
	v_max_f32_e32 v52, 0, v52
	v_mul_f32_e32 v51, v51, v51
	v_mul_f32_e32 v52, v52, v52
	v_max_f32_e32 v44, v44, v44
	v_max_f32_e32 v44, 0, v44
	v_max_f32_e32 v41, v41, v41
	v_max_f32_e32 v42, v42, v42
	v_max_f32_e32 v41, 0, v41
	v_max_f32_e32 v40, v40, v40
	v_mul_f32_e32 v41, v41, v41
	v_max_f32_e32 v40, 0, v40
	v_max_f32_e32 v43, v43, v43
	v_mul_f32_e32 v40, v40, v40
	v_max_f32_e32 v43, 0, v43
	v_max_f32_e32 v32, v32, v32
	v_max_f32_e32 v33, v33, v33
	v_max_f32_e32 v34, v34, v34
	v_mul_f32_e32 v43, v43, v43
	v_max_f32_e32 v32, 0, v32
	v_max_f32_e32 v33, 0, v33
	v_max_f32_e32 v34, 0, v34
	v_mul_f32_e32 v32, v32, v32
	v_mul_f32_e32 v33, v33, v33
	v_mul_f32_e32 v34, v34, v34
	v_max_f32_e32 v35, v35, v35
	v_max_f32_e32 v36, v36, v36
	v_max_f32_e32 v35, 0, v35
	v_max_f32_e32 v36, 0, v36
	v_mul_f32_e32 v35, v35, v35
	v_mul_f32_e32 v36, v36, v36
	v_max_f32_e32 v28, v28, v28
	v_max_f32_e32 v28, 0, v28
	v_max_f32_e32 v25, v25, v25
	v_max_f32_e32 v26, v26, v26
	v_max_f32_e32 v25, 0, v25
	v_max_f32_e32 v24, v24, v24
	v_mul_f32_e32 v25, v25, v25
	v_max_f32_e32 v24, 0, v24
	v_max_f32_e32 v27, v27, v27
	v_mul_f32_e32 v24, v24, v24
	v_max_f32_e32 v27, 0, v27
	v_max_f32_e32 v16, v16, v16
	v_max_f32_e32 v17, v17, v17
	v_max_f32_e32 v18, v18, v18
	v_mul_f32_e32 v27, v27, v27
	v_max_f32_e32 v16, 0, v16
	v_max_f32_e32 v17, 0, v17
	v_max_f32_e32 v18, 0, v18
	v_mul_f32_e32 v16, v16, v16
	v_mul_f32_e32 v17, v17, v17
	v_mul_f32_e32 v18, v18, v18
	v_max_f32_e32 v19, v19, v19
	v_max_f32_e32 v20, v20, v20
	v_max_f32_e32 v19, 0, v19
	v_max_f32_e32 v20, 0, v20
	v_mul_f32_e32 v19, v19, v19
	v_mul_f32_e32 v20, v20, v20
	v_max_f32_e32 v12, v12, v12
	v_max_f32_e32 v12, 0, v12
	v_max_f32_e32 v9, v9, v9
	v_max_f32_e32 v10, v10, v10
	v_max_f32_e32 v9, 0, v9
	v_max_f32_e32 v8, v8, v8
	v_mul_f32_e32 v9, v9, v9
	s_waitcnt vmcnt(3)
	v_mov_b32_e32 v94, v99
	v_mov_b32_e32 v95, v100
	v_mov_b32_e32 v99, v101
	s_waitcnt vmcnt(2)
	v_mov_b32_e32 v96, v103
	v_mov_b32_e32 v97, v104
	v_mov_b32_e32 v103, v105
	v_pk_add_f32 v[94:95], v[94:95], v[98:99]
	v_pk_add_f32 v[96:97], v[96:97], v[102:103]
	v_pk_add_f32 v[94:95], v[94:95], v[94:95] op_sel:[0,1] op_sel_hi:[1,0]
	v_pk_add_f32 v[96:97], v[96:97], v[96:97] op_sel:[0,1] op_sel_hi:[1,0]
	s_waitcnt vmcnt(1)
	v_add_f32_e32 v100, v106, v107
	v_add_f32_e32 v104, v108, v109
	s_waitcnt vmcnt(0)
	v_mov_b32_e32 v101, v112
	v_mov_b32_e32 v105, v113
	v_mov_b32_e32 v95, v110
	v_mov_b32_e32 v97, v111
	v_pk_add_f32 v[98:99], v[100:101], v[104:105]
	v_pk_add_f32 v[94:95], v[94:95], v[96:97]
	v_mul_f32_e32 v101, v79, v79
	v_pk_add_f32 v[94:95], v[94:95], v[98:99]
	v_mul_f32_e32 v102, v75, v75
	v_add_f32_e32 v91, v94, v95
	v_fmamk_f32 v91, v91, 0x3a800000, v176
	v_mul_f32_e32 v94, 0x4b800000, v91
	v_cmp_gt_f32_e32 vcc, s11, v91
	v_max_f32_e32 v8, 0, v8
	v_max_f32_e32 v11, v11, v11
	v_cndmask_b32_e32 v91, v91, v94, vcc
	v_rsq_f32_e32 v91, v91
	v_lshl_add_u64 v[94:95], v[92:93], 0, v[146:147]
	v_mul_f32_e32 v8, v8, v8
	v_max_f32_e32 v11, 0, v11
	v_mul_f32_e32 v92, 0x45800000, v91
	v_cndmask_b32_e32 v91, v91, v92, vcc
	v_pk_mul_f32 v[96:97], v[90:91], v[90:91]
	v_max_f32_e32 v0, v0, v0
	v_mul_f32_e32 v90, v117, v97
	v_mul_f32_e32 v92, v116, v97
	v_mul_f32_e32 v91, v118, v97
	v_mul_f32_e32 v93, v119, v97
	v_cvt_pk_bf16_f32 v90, v90, v91
	v_mul_f32_e32 v98, v120, v97
	v_mul_f32_e32 v96, v96, v97
	v_mul_f32_e32 v99, v121, v97
	v_mul_f32_e32 v100, v122, v97
	v_cvt_pk_bf16_f32 v91, v98, v99
	v_cvt_pk_bf16_f32 v92, v92, v93
	v_cvt_pk_bf16_f32 v93, v96, v100
	global_store_dwordx4 v[94:95], v[90:93], off
	v_or_b32_e32 v98, 48, v148
	v_mul_f32_e32 v86, v86, v97
	v_mul_f32_e32 v90, v82, v97
	v_max_f32_e32 v82, v87, v87
	v_mul_f32_e32 v87, v83, v97
	v_max_f32_e32 v83, v88, v88
	v_max_f32_e32 v82, 0, v82
	v_max_f32_e32 v83, 0, v83
	v_mul_f32_e32 v88, v84, v97
	v_max_f32_e32 v84, v89, v89
	v_mul_f32_e32 v82, v82, v82
	v_mul_f32_e32 v83, v83, v83
	v_max_f32_e32 v84, 0, v84
	v_mul_f32_e32 v82, v82, v97
	v_mul_f32_e32 v83, v83, v97
	v_mul_f32_e32 v84, v84, v84
	v_mul_f32_e32 v84, v84, v97
	v_mul_f32_e32 v85, v85, v97
	v_cvt_pk_bf16_f32 v82, v86, v82
	v_cvt_pk_bf16_f32 v83, v83, v84
	v_ashrrev_i32_e32 v99, 31, v98
	v_cvt_pk_bf16_f32 v84, v90, v87
	v_cvt_pk_bf16_f32 v85, v88, v85
	global_store_dwordx4 v[94:95], v[82:85], off offset:256
	v_max_f32_e32 v100, 0, v74
	v_max_f32_e32 v74, 0, v76
	v_lshlrev_b64 v[82:83], 6, v[98:99]
	v_lshl_add_u64 v[94:95], s[28:29], 0, v[82:83]
	global_load_dwordx4 v[82:85], v[94:95], off
	global_load_dwordx4 v[86:89], v[94:95], off offset:16
	global_load_dwordx4 v[90:93], v[94:95], off offset:32
	s_nop 0
	global_load_dwordx4 v[94:97], v[94:95], off offset:48
	v_mul_f32_e32 v76, v78, v78
	v_lshlrev_b64 v[78:79], 13, v[98:99]
	v_lshl_add_u64 v[78:79], s[80:81], 0, v[78:79]
	v_lshl_add_u64 v[78:79], v[78:79], 0, s[54:55]
	v_mul_f32_e32 v100, v100, v100
	v_lshl_add_u64 v[78:79], v[78:79], 0, s[76:77]
	v_lshl_add_u64 v[78:79], v[78:79], 0, v[146:147]
	v_max_f32_e32 v1, v1, v1
	v_max_f32_e32 v2, v2, v2
	v_mul_f32_e32 v11, v11, v11
	v_max_f32_e32 v0, 0, v0
	v_max_f32_e32 v1, 0, v1
	v_max_f32_e32 v2, 0, v2
	v_mul_f32_e32 v0, v0, v0
	v_mul_f32_e32 v1, v1, v1
	v_mul_f32_e32 v2, v2, v2
	v_max_f32_e32 v3, v3, v3
	v_max_f32_e32 v4, v4, v4
	v_max_f32_e32 v3, 0, v3
	v_max_f32_e32 v4, 0, v4
	v_mul_f32_e32 v3, v3, v3
	v_readlane_b32 s70, v255, 26
	v_readlane_b32 s74, v255, 32
	v_mul_f32_e32 v4, v4, v4
	s_mov_b64 s[4:5], -1
	v_readlane_b32 s71, v255, 27
	v_readlane_b32 s75, v255, 33
	s_movk_i32 s78, 0xf800
	s_waitcnt vmcnt(3)
	v_mov_b32_e32 v98, v83
	v_mov_b32_e32 v99, v84
	v_mov_b32_e32 v83, v85
	s_waitcnt vmcnt(2)
	v_mov_b32_e32 v84, v87
	v_mov_b32_e32 v85, v88
	v_mov_b32_e32 v87, v89
	v_pk_add_f32 v[82:83], v[98:99], v[82:83]
	v_pk_add_f32 v[84:85], v[84:85], v[86:87]
	v_pk_add_f32 v[82:83], v[82:83], v[82:83] op_sel:[0,1] op_sel_hi:[1,0]
	v_pk_add_f32 v[84:85], v[84:85], v[84:85] op_sel:[0,1] op_sel_hi:[1,0]
	s_waitcnt vmcnt(1)
	v_add_f32_e32 v88, v90, v91
	v_add_f32_e32 v90, v92, v93
	s_waitcnt vmcnt(0)
	v_mov_b32_e32 v89, v96
	v_mov_b32_e32 v91, v97
	v_mov_b32_e32 v83, v94
	v_mov_b32_e32 v85, v95
	v_pk_add_f32 v[86:87], v[88:89], v[90:91]
	v_pk_add_f32 v[82:83], v[82:83], v[84:85]
	s_nop 0
	v_pk_add_f32 v[82:83], v[82:83], v[86:87]
	s_nop 0
	v_add_f32_e32 v75, v82, v83
	v_fmamk_f32 v75, v75, 0x3a800000, v176
	v_mul_f32_e32 v82, 0x4b800000, v75
	v_cmp_gt_f32_e32 vcc, s11, v75
	s_nop 1
	v_cndmask_b32_e32 v75, v75, v82, vcc
	v_rsq_f32_e32 v75, v75
	s_nop 0
	v_mul_f32_e32 v82, 0x45800000, v75
	v_cndmask_b32_e32 v75, v75, v82, vcc
	v_pk_mul_f32 v[82:83], v[74:75], v[74:75]
	s_nop 0
	v_mul_f32_e32 v74, v76, v83
	v_mul_f32_e32 v76, v100, v83
	v_mul_f32_e32 v75, v101, v83
	v_mul_f32_e32 v77, v77, v83
	v_cvt_pk_bf16_f32 v74, v74, v75
	v_mul_f32_e32 v84, v102, v83
	v_mul_f32_e32 v80, v80, v83
	v_mul_f32_e32 v82, v82, v83
	v_mul_f32_e32 v81, v81, v83
	v_cvt_pk_bf16_f32 v75, v80, v81
	v_cvt_pk_bf16_f32 v76, v76, v84
	v_cvt_pk_bf16_f32 v77, v82, v77
	global_store_dwordx4 v[78:79], v[74:77], off
	v_add_u32_e32 v82, 0x80, v148
	v_mul_f32_e32 v70, v70, v83
	v_mul_f32_e32 v74, v66, v83
	v_max_f32_e32 v66, v71, v71
	v_mul_f32_e32 v71, v67, v83
	v_max_f32_e32 v67, v72, v72
	v_max_f32_e32 v66, 0, v66
	v_max_f32_e32 v67, 0, v67
	v_mul_f32_e32 v72, v68, v83
	v_max_f32_e32 v68, v73, v73
	v_mul_f32_e32 v66, v66, v66
	v_mul_f32_e32 v67, v67, v67
	v_max_f32_e32 v68, 0, v68
	v_mul_f32_e32 v66, v66, v83
	v_mul_f32_e32 v67, v67, v83
	v_mul_f32_e32 v68, v68, v68
	v_mul_f32_e32 v68, v68, v83
	v_mul_f32_e32 v69, v69, v83
	v_cvt_pk_bf16_f32 v66, v70, v66
	v_cvt_pk_bf16_f32 v67, v67, v68
	v_ashrrev_i32_e32 v83, 31, v82
	v_cvt_pk_bf16_f32 v68, v74, v71
	v_cvt_pk_bf16_f32 v69, v72, v69
	global_store_dwordx4 v[78:79], v[66:69], off offset:256
	s_nop 1
	v_lshlrev_b64 v[66:67], 6, v[82:83]
	v_lshl_add_u64 v[78:79], s[28:29], 0, v[66:67]
	global_load_dwordx4 v[66:69], v[78:79], off
	global_load_dwordx4 v[70:73], v[78:79], off offset:16
	global_load_dwordx4 v[74:77], v[78:79], off offset:32
	s_nop 0
	global_load_dwordx4 v[78:81], v[78:79], off offset:48
	v_lshlrev_b64 v[82:83], 13, v[82:83]
	v_lshl_add_u64 v[82:83], s[80:81], 0, v[82:83]
	s_waitcnt vmcnt(3)
	v_mov_b32_e32 v84, v67
	v_mov_b32_e32 v85, v68
	v_mov_b32_e32 v67, v69
	s_waitcnt vmcnt(2)
	v_mov_b32_e32 v68, v71
	v_mov_b32_e32 v69, v72
	v_mov_b32_e32 v71, v73
	v_pk_add_f32 v[66:67], v[84:85], v[66:67]
	v_pk_add_f32 v[68:69], v[68:69], v[70:71]
	v_pk_add_f32 v[66:67], v[66:67], v[66:67] op_sel:[0,1] op_sel_hi:[1,0]
	v_pk_add_f32 v[68:69], v[68:69], v[68:69] op_sel:[0,1] op_sel_hi:[1,0]
	s_waitcnt vmcnt(1)
	v_add_f32_e32 v72, v74, v75
	v_add_f32_e32 v74, v76, v77
	s_waitcnt vmcnt(0)
	v_mov_b32_e32 v73, v80
	v_mov_b32_e32 v75, v81
	v_mov_b32_e32 v67, v78
	v_mov_b32_e32 v69, v79
	v_pk_add_f32 v[70:71], v[72:73], v[74:75]
	v_pk_add_f32 v[66:67], v[66:67], v[68:69]
	s_nop 0
	v_pk_add_f32 v[66:67], v[66:67], v[70:71]
	v_mul_f32_e32 v70, v60, v60
	v_add_f32_e32 v66, v66, v67
	v_fmamk_f32 v66, v66, 0x3a800000, v176
	v_mul_f32_e32 v67, 0x4b800000, v66
	v_cmp_gt_f32_e32 vcc, s11, v66
	v_max_f32_e32 v60, v61, v61
	v_max_f32_e32 v60, 0, v60
	v_cndmask_b32_e32 v66, v66, v67, vcc
	v_rsq_f32_e32 v68, v66
	v_mul_f32_e32 v71, v60, v60
	v_max_f32_e32 v60, v62, v62
	v_max_f32_e32 v60, 0, v60
	v_mul_f32_e32 v69, 0x45800000, v68
	v_cndmask_b32_e32 v69, v68, v69, vcc
	v_max_f32_e32 v68, 0, v58
	v_mul_f32_e32 v58, v60, v60
	v_pk_mul_f32 v[60:61], v[68:69], v[68:69]
	v_lshl_add_u64 v[66:67], v[82:83], 0, s[54:55]
	v_mul_f32_e32 v69, v57, v61
	v_mul_f32_e32 v57, v58, v61
	v_max_f32_e32 v58, v63, v63
	v_max_f32_e32 v58, 0, v58
	v_lshl_add_u64 v[66:67], v[66:67], 0, s[76:77]
	v_mul_f32_e32 v68, v56, v61
	v_mul_f32_e32 v56, v71, v61
	v_mul_f32_e32 v58, v58, v58
	v_lshl_add_u64 v[66:67], v[66:67], 0, v[146:147]
	v_mul_f32_e32 v62, v70, v61
	v_mul_f32_e32 v58, v58, v61
	v_mul_f32_e32 v59, v59, v61
	v_cvt_pk_bf16_f32 v56, v62, v56
	v_mul_f32_e32 v60, v60, v61
	v_cvt_pk_bf16_f32 v57, v57, v58
	v_cvt_pk_bf16_f32 v58, v68, v69
	v_cvt_pk_bf16_f32 v59, v60, v59
	global_store_dwordx4 v[66:67], v[56:59], off
	v_mul_f32_e32 v51, v51, v61
	v_mul_f32_e32 v52, v52, v61
	v_mul_f32_e32 v56, v48, v61
	v_max_f32_e32 v48, v53, v53
	v_mul_f32_e32 v53, v49, v61
	v_max_f32_e32 v49, v54, v54
	v_mul_f32_e32 v54, v50, v61
	v_max_f32_e32 v50, v55, v55
	v_max_f32_e32 v48, 0, v48
	v_max_f32_e32 v49, 0, v49
	v_max_f32_e32 v50, 0, v50
	v_mul_f32_e32 v48, v48, v48
	v_mul_f32_e32 v49, v49, v49
	v_mul_f32_e32 v50, v50, v50
	v_mul_f32_e32 v48, v48, v61
	v_mul_f32_e32 v49, v49, v61
	v_mul_f32_e32 v50, v50, v61
	v_cvt_pk_bf16_f32 v48, v52, v48
	v_cvt_pk_bf16_f32 v49, v49, v50
	v_cvt_pk_bf16_f32 v50, v56, v53
	v_cvt_pk_bf16_f32 v51, v54, v51
	global_store_dwordx4 v[66:67], v[48:51], off offset:256
	v_add_u32_e32 v66, 0x90, v148
	v_ashrrev_i32_e32 v67, 31, v66
	v_lshlrev_b64 v[48:49], 6, v[66:67]
	v_lshl_add_u64 v[60:61], s[28:29], 0, v[48:49]
	global_load_dwordx4 v[48:51], v[60:61], off
	global_load_dwordx4 v[52:55], v[60:61], off offset:16
	global_load_dwordx4 v[56:59], v[60:61], off offset:32
	s_nop 0
	global_load_dwordx4 v[60:63], v[60:61], off offset:48
	v_lshlrev_b64 v[66:67], 13, v[66:67]
	v_lshl_add_u64 v[66:67], s[80:81], 0, v[66:67]
	s_waitcnt vmcnt(3)
	v_mov_b32_e32 v68, v49
	v_mov_b32_e32 v69, v50
	v_mov_b32_e32 v49, v51
	s_waitcnt vmcnt(2)
	v_mov_b32_e32 v50, v53
	v_mov_b32_e32 v51, v54
	v_mov_b32_e32 v53, v55
	v_pk_add_f32 v[48:49], v[68:69], v[48:49]
	v_pk_add_f32 v[50:51], v[50:51], v[52:53]
	v_pk_add_f32 v[48:49], v[48:49], v[48:49] op_sel:[0,1] op_sel_hi:[1,0]
	v_pk_add_f32 v[50:51], v[50:51], v[50:51] op_sel:[0,1] op_sel_hi:[1,0]
	s_waitcnt vmcnt(1)
	v_add_f32_e32 v52, v56, v57
	v_add_f32_e32 v54, v58, v59
	s_waitcnt vmcnt(0)
	v_mov_b32_e32 v49, v60
	v_mov_b32_e32 v51, v61
	v_mov_b32_e32 v53, v62
	v_mov_b32_e32 v55, v63
	v_pk_add_f32 v[48:49], v[48:49], v[50:51]
	v_pk_add_f32 v[50:51], v[52:53], v[54:55]
	v_mul_f32_e32 v52, v44, v44
	v_pk_add_f32 v[48:49], v[48:49], v[50:51]
	v_max_f32_e32 v44, v45, v45
	v_add_f32_e32 v48, v48, v49
	v_fmamk_f32 v48, v48, 0x3a800000, v176
	v_mul_f32_e32 v49, 0x4b800000, v48
	v_cmp_gt_f32_e32 vcc, s11, v48
	v_max_f32_e32 v44, 0, v44
	v_mul_f32_e32 v53, v44, v44
	v_cndmask_b32_e32 v48, v48, v49, vcc
	v_rsq_f32_e32 v50, v48
	v_max_f32_e32 v44, v46, v46
	v_max_f32_e32 v44, 0, v44
	v_lshl_add_u64 v[48:49], v[66:67], 0, s[54:55]
	v_mul_f32_e32 v51, 0x45800000, v50
	v_cndmask_b32_e32 v51, v50, v51, vcc
	v_max_f32_e32 v50, 0, v42
	v_mul_f32_e32 v42, v44, v44
	v_pk_mul_f32 v[44:45], v[50:51], v[50:51]
	v_lshl_add_u64 v[48:49], v[48:49], 0, s[76:77]
	v_mul_f32_e32 v51, v41, v45
	v_mul_f32_e32 v41, v42, v45
	v_max_f32_e32 v42, v47, v47
	v_max_f32_e32 v42, 0, v42
	v_mul_f32_e32 v50, v40, v45
	v_mul_f32_e32 v40, v53, v45
	v_mul_f32_e32 v42, v42, v42
	v_lshl_add_u64 v[48:49], v[48:49], 0, v[146:147]
	v_mul_f32_e32 v46, v52, v45
	v_mul_f32_e32 v42, v42, v45
	v_mul_f32_e32 v43, v43, v45
	v_cvt_pk_bf16_f32 v40, v46, v40
	v_mul_f32_e32 v44, v44, v45
	v_cvt_pk_bf16_f32 v41, v41, v42
	v_cvt_pk_bf16_f32 v42, v50, v51
	v_cvt_pk_bf16_f32 v43, v44, v43
	global_store_dwordx4 v[48:49], v[40:43], off
	v_mul_f32_e32 v35, v35, v45
	v_mul_f32_e32 v36, v36, v45
	v_mul_f32_e32 v40, v32, v45
	v_max_f32_e32 v32, v37, v37
	v_mul_f32_e32 v37, v33, v45
	v_max_f32_e32 v33, v38, v38
	v_mul_f32_e32 v38, v34, v45
	v_max_f32_e32 v34, v39, v39
	v_max_f32_e32 v32, 0, v32
	v_max_f32_e32 v33, 0, v33
	v_max_f32_e32 v34, 0, v34
	v_mul_f32_e32 v32, v32, v32
	v_mul_f32_e32 v33, v33, v33
	v_mul_f32_e32 v34, v34, v34
	v_mul_f32_e32 v32, v32, v45
	v_mul_f32_e32 v33, v33, v45
	v_mul_f32_e32 v34, v34, v45
	v_cvt_pk_bf16_f32 v32, v36, v32
	v_cvt_pk_bf16_f32 v33, v33, v34
	v_cvt_pk_bf16_f32 v34, v40, v37
	v_cvt_pk_bf16_f32 v35, v38, v35
	global_store_dwordx4 v[48:49], v[32:35], off offset:256
	v_add_u32_e32 v48, 0xa0, v148
	v_ashrrev_i32_e32 v49, 31, v48
	v_lshlrev_b64 v[32:33], 6, v[48:49]
	v_lshl_add_u64 v[44:45], s[28:29], 0, v[32:33]
	global_load_dwordx4 v[32:35], v[44:45], off
	global_load_dwordx4 v[36:39], v[44:45], off offset:16
	global_load_dwordx4 v[40:43], v[44:45], off offset:32
	s_nop 0
	global_load_dwordx4 v[44:47], v[44:45], off offset:48
	v_lshlrev_b64 v[48:49], 13, v[48:49]
	v_lshl_add_u64 v[48:49], s[80:81], 0, v[48:49]
	s_waitcnt vmcnt(3)
	v_mov_b32_e32 v50, v33
	v_mov_b32_e32 v51, v34
	v_mov_b32_e32 v33, v35
	s_waitcnt vmcnt(2)
	v_mov_b32_e32 v34, v37
	v_mov_b32_e32 v35, v38
	v_mov_b32_e32 v37, v39
	v_pk_add_f32 v[32:33], v[50:51], v[32:33]
	v_pk_add_f32 v[34:35], v[34:35], v[36:37]
	v_pk_add_f32 v[32:33], v[32:33], v[32:33] op_sel:[0,1] op_sel_hi:[1,0]
	v_pk_add_f32 v[34:35], v[34:35], v[34:35] op_sel:[0,1] op_sel_hi:[1,0]
	s_waitcnt vmcnt(1)
	v_add_f32_e32 v36, v40, v41
	v_add_f32_e32 v38, v42, v43
	s_waitcnt vmcnt(0)
	v_mov_b32_e32 v33, v44
	v_mov_b32_e32 v35, v45
	v_mov_b32_e32 v37, v46
	v_mov_b32_e32 v39, v47
	v_pk_add_f32 v[32:33], v[32:33], v[34:35]
	v_pk_add_f32 v[34:35], v[36:37], v[38:39]
	v_mul_f32_e32 v36, v28, v28
	v_pk_add_f32 v[32:33], v[32:33], v[34:35]
	v_max_f32_e32 v28, v29, v29
	v_add_f32_e32 v32, v32, v33
	v_fmamk_f32 v32, v32, 0x3a800000, v176
	v_mul_f32_e32 v33, 0x4b800000, v32
	v_cmp_gt_f32_e32 vcc, s11, v32
	v_max_f32_e32 v28, 0, v28
	v_mul_f32_e32 v37, v28, v28
	v_cndmask_b32_e32 v32, v32, v33, vcc
	v_rsq_f32_e32 v34, v32
	v_max_f32_e32 v28, v30, v30
	v_max_f32_e32 v28, 0, v28
	v_lshl_add_u64 v[32:33], v[48:49], 0, s[54:55]
	v_mul_f32_e32 v35, 0x45800000, v34
	v_cndmask_b32_e32 v35, v34, v35, vcc
	v_max_f32_e32 v34, 0, v26
	v_mul_f32_e32 v26, v28, v28
	v_pk_mul_f32 v[28:29], v[34:35], v[34:35]
	v_lshl_add_u64 v[32:33], v[32:33], 0, s[76:77]
	v_mul_f32_e32 v35, v25, v29
	v_mul_f32_e32 v25, v26, v29
	v_max_f32_e32 v26, v31, v31
	v_max_f32_e32 v26, 0, v26
	v_mul_f32_e32 v34, v24, v29
	v_mul_f32_e32 v24, v37, v29
	v_mul_f32_e32 v26, v26, v26
	v_lshl_add_u64 v[32:33], v[32:33], 0, v[146:147]
	v_mul_f32_e32 v30, v36, v29
	v_mul_f32_e32 v26, v26, v29
	v_mul_f32_e32 v27, v27, v29
	v_cvt_pk_bf16_f32 v24, v30, v24
	v_mul_f32_e32 v28, v28, v29
	v_cvt_pk_bf16_f32 v25, v25, v26
	v_cvt_pk_bf16_f32 v26, v34, v35
	v_cvt_pk_bf16_f32 v27, v28, v27
	global_store_dwordx4 v[32:33], v[24:27], off
	v_mul_f32_e32 v19, v19, v29
	v_mul_f32_e32 v20, v20, v29
	v_mul_f32_e32 v24, v16, v29
	v_max_f32_e32 v16, v21, v21
	v_mul_f32_e32 v21, v17, v29
	v_max_f32_e32 v17, v22, v22
	v_mul_f32_e32 v22, v18, v29
	v_max_f32_e32 v18, v23, v23
	v_max_f32_e32 v16, 0, v16
	v_max_f32_e32 v17, 0, v17
	v_max_f32_e32 v18, 0, v18
	v_mul_f32_e32 v16, v16, v16
	v_mul_f32_e32 v17, v17, v17
	v_mul_f32_e32 v18, v18, v18
	v_mul_f32_e32 v16, v16, v29
	v_mul_f32_e32 v17, v17, v29
	v_mul_f32_e32 v18, v18, v29
	v_cvt_pk_bf16_f32 v16, v20, v16
	v_cvt_pk_bf16_f32 v17, v17, v18
	v_cvt_pk_bf16_f32 v18, v24, v21
	v_cvt_pk_bf16_f32 v19, v22, v19
	global_store_dwordx4 v[32:33], v[16:19], off offset:256
	v_add_u32_e32 v32, 0xb0, v148
	v_ashrrev_i32_e32 v33, 31, v32
	v_lshlrev_b64 v[16:17], 6, v[32:33]
	v_lshl_add_u64 v[28:29], s[28:29], 0, v[16:17]
	global_load_dwordx4 v[16:19], v[28:29], off
	global_load_dwordx4 v[20:23], v[28:29], off offset:16
	global_load_dwordx4 v[24:27], v[28:29], off offset:32
	s_nop 0
	global_load_dwordx4 v[28:31], v[28:29], off offset:48
	v_lshlrev_b64 v[32:33], 13, v[32:33]
	v_lshl_add_u64 v[32:33], s[80:81], 0, v[32:33]
	s_waitcnt vmcnt(3)
	v_mov_b32_e32 v34, v17
	v_mov_b32_e32 v35, v18
	v_mov_b32_e32 v17, v19
	s_waitcnt vmcnt(2)
	v_mov_b32_e32 v18, v21
	v_mov_b32_e32 v19, v22
	v_mov_b32_e32 v21, v23
	v_pk_add_f32 v[16:17], v[34:35], v[16:17]
	v_pk_add_f32 v[18:19], v[18:19], v[20:21]
	v_pk_add_f32 v[16:17], v[16:17], v[16:17] op_sel:[0,1] op_sel_hi:[1,0]
	v_pk_add_f32 v[18:19], v[18:19], v[18:19] op_sel:[0,1] op_sel_hi:[1,0]
	s_waitcnt vmcnt(1)
	v_add_f32_e32 v20, v24, v25
	v_add_f32_e32 v22, v26, v27
	s_waitcnt vmcnt(0)
	v_mov_b32_e32 v17, v28
	v_mov_b32_e32 v19, v29
	v_mov_b32_e32 v21, v30
	v_mov_b32_e32 v23, v31
	v_pk_add_f32 v[16:17], v[16:17], v[18:19]
	v_pk_add_f32 v[18:19], v[20:21], v[22:23]
	v_mul_f32_e32 v20, v12, v12
	v_pk_add_f32 v[16:17], v[16:17], v[18:19]
	v_max_f32_e32 v12, v13, v13
	v_add_f32_e32 v16, v16, v17
	v_fmamk_f32 v16, v16, 0x3a800000, v176
	v_mul_f32_e32 v17, 0x4b800000, v16
	v_cmp_gt_f32_e32 vcc, s11, v16
	v_max_f32_e32 v12, 0, v12
	v_mul_f32_e32 v21, v12, v12
	v_cndmask_b32_e32 v16, v16, v17, vcc
	v_rsq_f32_e32 v18, v16
	v_max_f32_e32 v12, v14, v14
	v_max_f32_e32 v12, 0, v12
	v_lshl_add_u64 v[16:17], v[32:33], 0, s[54:55]
	v_mul_f32_e32 v19, 0x45800000, v18
	v_cndmask_b32_e32 v19, v18, v19, vcc
	v_max_f32_e32 v18, 0, v10
	v_mul_f32_e32 v10, v12, v12
	v_pk_mul_f32 v[12:13], v[18:19], v[18:19]
	v_lshl_add_u64 v[16:17], v[16:17], 0, s[76:77]
	v_mul_f32_e32 v19, v9, v13
	v_mul_f32_e32 v9, v10, v13
	v_max_f32_e32 v10, v15, v15
	v_max_f32_e32 v10, 0, v10
	v_mul_f32_e32 v18, v8, v13
	v_mul_f32_e32 v8, v21, v13
	v_mul_f32_e32 v10, v10, v10
	v_lshl_add_u64 v[16:17], v[16:17], 0, v[146:147]
	v_mul_f32_e32 v14, v20, v13
	v_mul_f32_e32 v10, v10, v13
	v_mul_f32_e32 v11, v11, v13
	v_cvt_pk_bf16_f32 v8, v14, v8
	v_mul_f32_e32 v12, v12, v13
	v_cvt_pk_bf16_f32 v9, v9, v10
	v_cvt_pk_bf16_f32 v10, v18, v19
	v_cvt_pk_bf16_f32 v11, v12, v11
	global_store_dwordx4 v[16:17], v[8:11], off
	v_mul_f32_e32 v3, v3, v13
	s_andn2_b64 vcc, exec, s[38:39]
	v_mul_f32_e32 v8, v0, v13
	v_max_f32_e32 v0, v5, v5
	v_mul_f32_e32 v5, v1, v13
	v_max_f32_e32 v1, v6, v6
	v_mul_f32_e32 v6, v2, v13
	v_max_f32_e32 v2, v7, v7
	v_max_f32_e32 v0, 0, v0
	v_max_f32_e32 v1, 0, v1
	v_max_f32_e32 v2, 0, v2
	v_mul_f32_e32 v0, v0, v0
	v_mul_f32_e32 v1, v1, v1
	v_mul_f32_e32 v2, v2, v2
	v_mul_f32_e32 v0, v0, v13
	v_mul_f32_e32 v1, v1, v13
	v_mul_f32_e32 v2, v2, v13
	v_mul_f32_e32 v4, v4, v13
	v_cvt_pk_bf16_f32 v0, v4, v0
	v_cvt_pk_bf16_f32 v1, v1, v2
	v_cvt_pk_bf16_f32 v2, v8, v5
	v_cvt_pk_bf16_f32 v3, v6, v3
	global_store_dwordx4 v[16:17], v[0:3], off offset:256
.Lffn1_done:
	s_cbranch_vccnz .LBB0_29
	s_andn2_b64 vcc, exec, s[36:37]
	s_cbranch_vccnz .LBB0_28
	s_barrier
	s_branch .LBB0_28

.LBB0_69:
	v_readlane_b32 s36, v250, 25
	v_mbcnt_lo_u32_b32 v147, -1, 0
	v_mbcnt_hi_u32_b32 v147, -1, v147
	s_nop 1
	s_lshr_b32 s37, s36, 8
	s_bfe_u32 s36, s36, 0x20006
	v_and_b32_e32 v148, 15, v147
	v_lshrrev_b32_e32 v149, 4, v147
	s_lshl_b32 vcc_lo, s3, 8
	s_lshl_b32 s37, s37, 6
	s_add_u32 s37, s37, vcc_lo
	v_add_u32_e32 v148, s37, v148
	v_lshlrev_b32_e32 v139, 6, v148
	v_lshl_add_u32 v139, v149, 4, v139
	v_lshlrev_b32_e32 v138, 11, v148
	v_lshl_add_u32 v138, v149, 4, v138
	s_lshl_b32 s36, s36, 6
	v_add_u32_e32 v138, s36, v138
	s_lshl_b32 vcc_lo, s2, 9
	s_add_u32 s54, s80, vcc_lo
	s_addc_u32 s55, s81, 0
	v_readlane_b32 s2, v250, 23
	v_readlane_b32 s3, v250, 24
	s_nop 4
	global_load_dwordx4 v[154:157], v139, s[2:3]
	global_load_dwordx4 v[158:161], v139, s[2:3] offset:1024
	global_load_dwordx4 v[162:165], v139, s[2:3] offset:2048
	global_load_dwordx4 v[166:169], v139, s[2:3] offset:3072
	v_add_u32_e32 v139, 0x2000, v139
	s_waitcnt vmcnt(0)
	v_add_f32_e32 v154, v154, v155
	v_add_f32_e32 v156, v156, v157
	v_add_f32_e32 v147, v154, v156
	v_add_f32_e32 v158, v158, v159
	v_add_f32_e32 v160, v160, v161
	v_add_f32_e32 v148, v158, v160
	v_add_f32_e32 v162, v162, v163
	v_add_f32_e32 v164, v164, v165
	v_add_f32_e32 v149, v162, v164
	v_add_f32_e32 v166, v166, v167
	v_add_f32_e32 v168, v168, v169
	v_add_f32_e32 v171, v166, v168
	global_load_dwordx4 v[154:157], v139, s[2:3]
	global_load_dwordx4 v[158:161], v139, s[2:3] offset:1024
	global_load_dwordx4 v[162:165], v139, s[2:3] offset:2048
	global_load_dwordx4 v[166:169], v139, s[2:3] offset:3072
	v_mov_b32_e32 v170, v147
	s_nop 1
	v_permlane16_swap_b32_e32 v170, v147
	v_add_f32_e32 v147, v170, v147
	v_mov_b32_e32 v170, v148
	s_nop 1
	v_permlane16_swap_b32_e32 v170, v148
	v_add_f32_e32 v148, v170, v148
	v_mov_b32_e32 v170, v149
	s_nop 1
	v_permlane16_swap_b32_e32 v170, v149
	v_add_f32_e32 v149, v170, v149
	v_mov_b32_e32 v170, v171
	s_nop 1
	v_permlane16_swap_b32_e32 v170, v171
	v_add_f32_e32 v171, v170, v171
	v_mov_b32_e32 v170, v147
	s_nop 1
	v_permlane32_swap_b32_e32 v170, v147
	v_add_f32_e32 v147, v170, v147
	v_mov_b32_e32 v170, v148
	s_nop 1
	v_permlane32_swap_b32_e32 v170, v148
	v_add_f32_e32 v148, v170, v148
	v_mov_b32_e32 v170, v149
	s_nop 1
	v_permlane32_swap_b32_e32 v170, v149
	v_add_f32_e32 v149, v170, v149
	v_mov_b32_e32 v170, v171
	s_nop 1
	v_permlane32_swap_b32_e32 v170, v171
	v_add_f32_e32 v171, v170, v171
	v_fmamk_f32 v147, v147, 0x3a800000, v176
	v_fmamk_f32 v148, v148, 0x3a800000, v176
	v_fmamk_f32 v149, v149, 0x3a800000, v176
	v_fmamk_f32 v171, v171, 0x3a800000, v176
	v_rsq_f32_e32 v147, v147
	v_rsq_f32_e32 v148, v148
	v_rsq_f32_e32 v149, v149
	v_rsq_f32_e32 v171, v171
	s_nop 0
	v_mul_f32_e32 v147, 0x3db8aa3b, v147
	v_mul_f32_e32 v148, 0x3db8aa3b, v148
	v_mul_f32_e32 v149, 0x3db8aa3b, v149
	v_mul_f32_e32 v171, 0x3db8aa3b, v171
	s_waitcnt vmcnt(0)
	v_add_f32_e32 v154, v154, v155
	v_add_f32_e32 v156, v156, v157
	v_add_f32_e32 v154, v154, v156
	v_add_f32_e32 v158, v158, v159
	v_add_f32_e32 v160, v160, v161
	v_add_f32_e32 v158, v158, v160
	v_add_f32_e32 v162, v162, v163
	v_add_f32_e32 v164, v164, v165
	v_add_f32_e32 v162, v162, v164
	v_add_f32_e32 v166, v166, v167
	v_add_f32_e32 v168, v168, v169
	v_add_f32_e32 v166, v166, v168
	v_mov_b32_e32 v170, v154
	s_nop 1
	v_permlane16_swap_b32_e32 v170, v154
	v_add_f32_e32 v154, v170, v154
	v_mov_b32_e32 v170, v158
	s_nop 1
	v_permlane16_swap_b32_e32 v170, v158
	v_add_f32_e32 v158, v170, v158
	v_mov_b32_e32 v170, v162
	s_nop 1
	v_permlane16_swap_b32_e32 v170, v162
	v_add_f32_e32 v162, v170, v162
	v_mov_b32_e32 v170, v166
	s_nop 1
	v_permlane16_swap_b32_e32 v170, v166
	v_add_f32_e32 v166, v170, v166
	v_mov_b32_e32 v170, v154
	s_nop 1
	v_permlane32_swap_b32_e32 v170, v154
	v_add_f32_e32 v154, v170, v154
	v_mov_b32_e32 v170, v158
	s_nop 1
	v_permlane32_swap_b32_e32 v170, v158
	v_add_f32_e32 v158, v170, v158
	v_mov_b32_e32 v170, v162
	s_nop 1
	v_permlane32_swap_b32_e32 v170, v162
	v_add_f32_e32 v162, v170, v162
	v_mov_b32_e32 v170, v166
	s_nop 1
	v_permlane32_swap_b32_e32 v170, v166
	v_add_f32_e32 v166, v170, v166
	v_fmamk_f32 v154, v154, 0x3a800000, v176
	v_fmamk_f32 v158, v158, 0x3a800000, v176
	v_fmamk_f32 v162, v162, 0x3a800000, v176
	v_fmamk_f32 v166, v166, 0x3a800000, v176
	v_rsq_f32_e32 v154, v154
	v_rsq_f32_e32 v158, v158
	v_rsq_f32_e32 v162, v162
	v_rsq_f32_e32 v166, v166
	s_nop 0
	v_mul_f32_e32 v154, 0x3db8aa3b, v154
	v_mul_f32_e32 v158, 0x3db8aa3b, v158
	v_mul_f32_e32 v162, 0x3db8aa3b, v162
	v_mul_f32_e32 v166, 0x3db8aa3b, v166
	v_mul_f32_e32 v126, v126, v147
	v_mul_f32_e32 v127, v127, v147
	v_mul_f32_e32 v128, v128, v147
	v_mul_f32_e32 v129, v129, v147
	v_mul_f32_e32 v122, v122, v147
	v_mul_f32_e32 v123, v123, v147
	v_mul_f32_e32 v124, v124, v147
	v_mul_f32_e32 v125, v125, v147
	v_cvt_pk_bf16_f32 v126, v126, v127
	v_cvt_pk_bf16_f32 v127, v128, v129
	v_cvt_pk_bf16_f32 v128, v122, v123
	v_cvt_pk_bf16_f32 v129, v124, v125
	global_store_dwordx4 v138, v[126:129], s[54:55]
	v_mul_f32_e32 v118, v118, v147
	v_mul_f32_e32 v119, v119, v147
	v_mul_f32_e32 v120, v120, v147
	v_mul_f32_e32 v121, v121, v147
	v_mul_f32_e32 v114, v114, v147
	v_mul_f32_e32 v115, v115, v147
	v_mul_f32_e32 v116, v116, v147
	v_mul_f32_e32 v117, v117, v147
	v_cvt_pk_bf16_f32 v118, v118, v119
	v_cvt_pk_bf16_f32 v119, v120, v121
	v_cvt_pk_bf16_f32 v120, v114, v115
	v_cvt_pk_bf16_f32 v121, v116, v117
	global_store_dwordx4 v138, v[118:121], s[54:55] offset:256
	v_add_u32_e32 v138, 0x8000, v138
	v_mul_f32_e32 v110, v110, v148
	v_mul_f32_e32 v111, v111, v148
	v_mul_f32_e32 v112, v112, v148
	v_mul_f32_e32 v113, v113, v148
	v_mul_f32_e32 v106, v106, v148
	v_mul_f32_e32 v107, v107, v148
	v_mul_f32_e32 v108, v108, v148
	v_mul_f32_e32 v109, v109, v148
	v_cvt_pk_bf16_f32 v110, v110, v111
	v_cvt_pk_bf16_f32 v111, v112, v113
	v_cvt_pk_bf16_f32 v112, v106, v107
	v_cvt_pk_bf16_f32 v113, v108, v109
	global_store_dwordx4 v138, v[110:113], s[54:55]
	v_mul_f32_e32 v102, v102, v148
	v_mul_f32_e32 v103, v103, v148
	v_mul_f32_e32 v104, v104, v148
	v_mul_f32_e32 v105, v105, v148
	v_mul_f32_e32 v98, v98, v148
	v_mul_f32_e32 v99, v99, v148
	v_mul_f32_e32 v100, v100, v148
	v_mul_f32_e32 v101, v101, v148
	v_cvt_pk_bf16_f32 v102, v102, v103
	v_cvt_pk_bf16_f32 v103, v104, v105
	v_cvt_pk_bf16_f32 v104, v98, v99
	v_cvt_pk_bf16_f32 v105, v100, v101
	global_store_dwordx4 v138, v[102:105], s[54:55] offset:256
	v_add_u32_e32 v138, 0x8000, v138
	v_mul_f32_e32 v94, v94, v149
	v_mul_f32_e32 v95, v95, v149
	v_mul_f32_e32 v96, v96, v149
	v_mul_f32_e32 v97, v97, v149
	v_mul_f32_e32 v90, v90, v149
	v_mul_f32_e32 v91, v91, v149
	v_mul_f32_e32 v92, v92, v149
	v_mul_f32_e32 v93, v93, v149
	v_cvt_pk_bf16_f32 v94, v94, v95
	v_cvt_pk_bf16_f32 v95, v96, v97
	v_cvt_pk_bf16_f32 v96, v90, v91
	v_cvt_pk_bf16_f32 v97, v92, v93
	global_store_dwordx4 v138, v[94:97], s[54:55]
	v_mul_f32_e32 v86, v86, v149
	v_mul_f32_e32 v87, v87, v149
	v_mul_f32_e32 v88, v88, v149
	v_mul_f32_e32 v89, v89, v149
	v_mul_f32_e32 v82, v82, v149
	v_mul_f32_e32 v83, v83, v149
	v_mul_f32_e32 v84, v84, v149
	v_mul_f32_e32 v85, v85, v149
	v_cvt_pk_bf16_f32 v86, v86, v87
	v_cvt_pk_bf16_f32 v87, v88, v89
	v_cvt_pk_bf16_f32 v88, v82, v83
	v_cvt_pk_bf16_f32 v89, v84, v85
	global_store_dwordx4 v138, v[86:89], s[54:55] offset:256
	v_add_u32_e32 v138, 0x8000, v138
	v_mul_f32_e32 v78, v78, v171
	v_mul_f32_e32 v79, v79, v171
	v_mul_f32_e32 v80, v80, v171
	v_mul_f32_e32 v81, v81, v171
	v_mul_f32_e32 v74, v74, v171
	v_mul_f32_e32 v75, v75, v171
	v_mul_f32_e32 v76, v76, v171
	v_mul_f32_e32 v77, v77, v171
	v_cvt_pk_bf16_f32 v78, v78, v79
	v_cvt_pk_bf16_f32 v79, v80, v81
	v_cvt_pk_bf16_f32 v80, v74, v75
	v_cvt_pk_bf16_f32 v81, v76, v77
	global_store_dwordx4 v138, v[78:81], s[54:55]
	v_mul_f32_e32 v70, v70, v171
	v_mul_f32_e32 v71, v71, v171
	v_mul_f32_e32 v72, v72, v171
	v_mul_f32_e32 v73, v73, v171
	v_mul_f32_e32 v66, v66, v171
	v_mul_f32_e32 v67, v67, v171
	v_mul_f32_e32 v68, v68, v171
	v_mul_f32_e32 v69, v69, v171
	v_cvt_pk_bf16_f32 v70, v70, v71
	v_cvt_pk_bf16_f32 v71, v72, v73
	v_cvt_pk_bf16_f32 v72, v66, v67
	v_cvt_pk_bf16_f32 v73, v68, v69
	global_store_dwordx4 v138, v[70:73], s[54:55] offset:256
	v_add_u32_e32 v138, 0x28000, v138
	v_mul_f32_e32 v60, v60, v154
	v_mul_f32_e32 v61, v61, v154
	v_mul_f32_e32 v62, v62, v154
	v_mul_f32_e32 v63, v63, v154
	v_mul_f32_e32 v56, v56, v154
	v_mul_f32_e32 v57, v57, v154
	v_mul_f32_e32 v58, v58, v154
	v_mul_f32_e32 v59, v59, v154
	v_cvt_pk_bf16_f32 v60, v60, v61
	v_cvt_pk_bf16_f32 v61, v62, v63
	v_cvt_pk_bf16_f32 v62, v56, v57
	v_cvt_pk_bf16_f32 v63, v58, v59
	global_store_dwordx4 v138, v[60:63], s[54:55]
	v_mul_f32_e32 v52, v52, v154
	v_mul_f32_e32 v53, v53, v154
	v_mul_f32_e32 v54, v54, v154
	v_mul_f32_e32 v55, v55, v154
	v_mul_f32_e32 v48, v48, v154
	v_mul_f32_e32 v49, v49, v154
	v_mul_f32_e32 v50, v50, v154
	v_mul_f32_e32 v51, v51, v154
	v_cvt_pk_bf16_f32 v52, v52, v53
	v_cvt_pk_bf16_f32 v53, v54, v55
	v_cvt_pk_bf16_f32 v54, v48, v49
	v_cvt_pk_bf16_f32 v55, v50, v51
	global_store_dwordx4 v138, v[52:55], s[54:55] offset:256
	v_add_u32_e32 v138, 0x8000, v138
	v_mul_f32_e32 v44, v44, v158
	v_mul_f32_e32 v45, v45, v158
	v_mul_f32_e32 v46, v46, v158
	v_mul_f32_e32 v47, v47, v158
	v_mul_f32_e32 v40, v40, v158
	v_mul_f32_e32 v41, v41, v158
	v_mul_f32_e32 v42, v42, v158
	v_mul_f32_e32 v43, v43, v158
	v_cvt_pk_bf16_f32 v44, v44, v45
	v_cvt_pk_bf16_f32 v45, v46, v47
	v_cvt_pk_bf16_f32 v46, v40, v41
	v_cvt_pk_bf16_f32 v47, v42, v43
	global_store_dwordx4 v138, v[44:47], s[54:55]
	v_mul_f32_e32 v36, v36, v158
	v_mul_f32_e32 v37, v37, v158
	v_mul_f32_e32 v38, v38, v158
	v_mul_f32_e32 v39, v39, v158
	v_mul_f32_e32 v32, v32, v158
	v_mul_f32_e32 v33, v33, v158
	v_mul_f32_e32 v34, v34, v158
	v_mul_f32_e32 v35, v35, v158
	v_cvt_pk_bf16_f32 v36, v36, v37
	v_cvt_pk_bf16_f32 v37, v38, v39
	v_cvt_pk_bf16_f32 v38, v32, v33
	v_cvt_pk_bf16_f32 v39, v34, v35
	global_store_dwordx4 v138, v[36:39], s[54:55] offset:256
	v_add_u32_e32 v138, 0x8000, v138
	v_mul_f32_e32 v28, v28, v162
	v_mul_f32_e32 v29, v29, v162
	v_mul_f32_e32 v30, v30, v162
	v_mul_f32_e32 v31, v31, v162
	v_mul_f32_e32 v24, v24, v162
	v_mul_f32_e32 v25, v25, v162
	v_mul_f32_e32 v26, v26, v162
	v_mul_f32_e32 v27, v27, v162
	v_cvt_pk_bf16_f32 v28, v28, v29
	v_cvt_pk_bf16_f32 v29, v30, v31
	v_cvt_pk_bf16_f32 v30, v24, v25
	v_cvt_pk_bf16_f32 v31, v26, v27
	global_store_dwordx4 v138, v[28:31], s[54:55]
	v_mul_f32_e32 v20, v20, v162
	v_mul_f32_e32 v21, v21, v162
	v_mul_f32_e32 v22, v22, v162
	v_mul_f32_e32 v23, v23, v162
	v_mul_f32_e32 v16, v16, v162
	v_mul_f32_e32 v17, v17, v162
	v_mul_f32_e32 v18, v18, v162
	v_mul_f32_e32 v19, v19, v162
	v_cvt_pk_bf16_f32 v20, v20, v21
	v_cvt_pk_bf16_f32 v21, v22, v23
	v_cvt_pk_bf16_f32 v22, v16, v17
	v_cvt_pk_bf16_f32 v23, v18, v19
	global_store_dwordx4 v138, v[20:23], s[54:55] offset:256
	v_add_u32_e32 v138, 0x8000, v138
	v_mul_f32_e32 v12, v12, v166
	v_mul_f32_e32 v13, v13, v166
	v_mul_f32_e32 v14, v14, v166
	v_mul_f32_e32 v15, v15, v166
	v_mul_f32_e32 v8, v8, v166
	v_mul_f32_e32 v9, v9, v166
	v_mul_f32_e32 v10, v10, v166
	v_mul_f32_e32 v11, v11, v166
	v_cvt_pk_bf16_f32 v12, v12, v13
	v_cvt_pk_bf16_f32 v13, v14, v15
	v_cvt_pk_bf16_f32 v14, v8, v9
	v_cvt_pk_bf16_f32 v15, v10, v11
	global_store_dwordx4 v138, v[12:15], s[54:55]
	v_mul_f32_e32 v4, v4, v166
	v_mul_f32_e32 v5, v5, v166
	v_mul_f32_e32 v6, v6, v166
	v_mul_f32_e32 v7, v7, v166
	v_mul_f32_e32 v0, v0, v166
	v_mul_f32_e32 v1, v1, v166
	v_mul_f32_e32 v2, v2, v166
	v_mul_f32_e32 v3, v3, v166
	v_cvt_pk_bf16_f32 v4, v4, v5
	v_cvt_pk_bf16_f32 v5, v6, v7
	v_cvt_pk_bf16_f32 v6, v0, v1
	v_cvt_pk_bf16_f32 v7, v2, v3
	global_store_dwordx4 v138, v[4:7], s[54:55] offset:256
	s_andn2_b64 vcc, exec, s[38:39]
	s_mov_b64 s[36:37], -1
	s_branch .Lxq_done
	s_lshl_b32 s2, s2, 8
	v_lshl_add_u32 v148, s3, 8, v151
	s_ashr_i32 s3, s2, 31
	v_ashrrev_i32_e32 v149, 31, v148
	s_lshl_b64 s[54:55], s[2:3], 1
	v_readlane_b32 s2, v250, 23
	v_lshlrev_b64 v[154:155], 6, v[148:149]
	v_readlane_b32 s3, v250, 24
	v_lshlrev_b64 v[138:139], 11, v[148:149]
	v_lshl_add_u64 v[138:139], s[80:81], 0, v[138:139]
	v_lshl_add_u64 v[166:167], s[2:3], 0, v[154:155]
	global_load_dwordx4 v[154:157], v[166:167], off offset:48
	global_load_dwordx4 v[158:161], v[166:167], off offset:32
	global_load_dwordx4 v[162:165], v[166:167], off offset:16
	s_nop 0
	global_load_dwordx4 v[166:169], v[166:167], off
	v_lshl_add_u64 v[138:139], v[138:139], 0, s[54:55]
	v_lshl_add_u64 v[138:139], v[138:139], 0, s[76:77]
	v_mov_b32_e32 v147, v64
	v_lshl_add_u64 v[138:139], v[138:139], 0, v[146:147]
	s_mov_b64 s[36:37], -1
	s_waitcnt vmcnt(0)
	v_add_f32_e32 v158, v158, v159
	v_add_f32_e32 v160, v160, v161
	v_mov_b32_e32 v170, v167
	v_mov_b32_e32 v171, v168
	v_mov_b32_e32 v167, v169
	v_mov_b32_e32 v168, v163
	v_mov_b32_e32 v169, v164
	v_mov_b32_e32 v163, v165
	v_pk_add_f32 v[166:167], v[170:171], v[166:167]
	v_pk_add_f32 v[162:163], v[168:169], v[162:163]
	v_pk_add_f32 v[166:167], v[166:167], v[166:167] op_sel:[0,1] op_sel_hi:[1,0]
	v_pk_add_f32 v[162:163], v[162:163], v[162:163] op_sel:[0,1] op_sel_hi:[1,0]
	v_mov_b32_e32 v167, v154
	v_mov_b32_e32 v163, v155
	v_mov_b32_e32 v159, v156
	v_mov_b32_e32 v161, v157
	v_pk_add_f32 v[154:155], v[166:167], v[162:163]
	v_pk_add_f32 v[156:157], v[158:159], v[160:161]
	s_nop 0
	v_pk_add_f32 v[154:155], v[154:155], v[156:157]
	s_nop 0
	v_add_f32_e32 v149, v154, v155
	v_fmamk_f32 v149, v149, 0x3a800000, v176
	v_cmp_gt_f32_e32 vcc, s11, v149
	v_mul_f32_e32 v154, 0x4b800000, v149
	s_nop 0
	v_cndmask_b32_e32 v149, v149, v154, vcc
	v_rsq_f32_e32 v149, v149
	s_nop 0
	v_mul_f32_e32 v154, 0x45800000, v149
	v_cndmask_b32_e32 v149, v149, v154, vcc
	v_mul_f32_e32 v154, 0x3db8aa3b, v149
	v_pk_mul_f32 v[128:129], v[128:129], v[154:155] op_sel_hi:[1,0]
	v_pk_mul_f32 v[126:127], v[126:127], v[154:155] op_sel_hi:[1,0]
	v_pk_mul_f32 v[156:157], v[124:125], v[154:155] op_sel_hi:[1,0]
	v_pk_mul_f32 v[124:125], v[122:123], v[154:155] op_sel_hi:[1,0]
	v_cvt_pk_bf16_f32 v122, v126, v127
	v_cvt_pk_bf16_f32 v123, v128, v129
	v_pk_mul_f32 v[120:121], v[120:121], v[154:155] op_sel_hi:[1,0]
	v_cvt_pk_bf16_f32 v124, v124, v125
	v_cvt_pk_bf16_f32 v125, v156, v157
	global_store_dwordx4 v[138:139], v[122:125], off
	v_pk_mul_f32 v[118:119], v[118:119], v[154:155] op_sel_hi:[1,0]
	s_nop 0
	v_pk_mul_f32 v[122:123], v[116:117], v[154:155] op_sel_hi:[1,0]
	v_pk_mul_f32 v[116:117], v[114:115], v[154:155] op_sel_hi:[1,0]
	v_cvt_pk_bf16_f32 v114, v118, v119
	v_cvt_pk_bf16_f32 v115, v120, v121
	s_nop 0
	v_cvt_pk_bf16_f32 v116, v116, v117
	v_cvt_pk_bf16_f32 v117, v122, v123
	global_store_dwordx4 v[138:139], v[114:117], off offset:256
	s_nop 1
	v_or_b32_e32 v116, 16, v148
	v_ashrrev_i32_e32 v117, 31, v116
	v_lshlrev_b64 v[114:115], 11, v[116:117]
	v_lshlrev_b64 v[116:117], 6, v[116:117]
	v_lshl_add_u64 v[128:129], s[2:3], 0, v[116:117]
	global_load_dwordx4 v[116:119], v[128:129], off offset:48
	global_load_dwordx4 v[120:123], v[128:129], off offset:32
	global_load_dwordx4 v[124:127], v[128:129], off offset:16
	global_load_dwordx4 v[154:157], v[128:129], off
	v_lshl_add_u64 v[114:115], s[80:81], 0, v[114:115]
	v_lshl_add_u64 v[114:115], v[114:115], 0, s[54:55]
	v_lshl_add_u64 v[114:115], v[114:115], 0, s[76:77]
	v_lshl_add_u64 v[114:115], v[114:115], 0, v[146:147]
	s_waitcnt vmcnt(2)
	v_add_f32_e32 v120, v120, v121
	s_waitcnt vmcnt(1)
	v_mov_b32_e32 v138, v125
	s_waitcnt vmcnt(0)
	v_mov_b32_e32 v128, v155
	v_mov_b32_e32 v129, v156
	v_mov_b32_e32 v155, v157
	v_mov_b32_e32 v139, v126
	v_mov_b32_e32 v125, v127
	v_pk_add_f32 v[128:129], v[128:129], v[154:155]
	v_pk_add_f32 v[124:125], v[138:139], v[124:125]
	v_pk_add_f32 v[128:129], v[128:129], v[128:129] op_sel:[0,1] op_sel_hi:[1,0]
	v_pk_add_f32 v[124:125], v[124:125], v[124:125] op_sel:[0,1] op_sel_hi:[1,0]
	v_add_f32_e32 v122, v122, v123
	v_mov_b32_e32 v129, v116
	v_mov_b32_e32 v125, v117
	v_mov_b32_e32 v121, v118
	v_mov_b32_e32 v123, v119
	v_pk_add_f32 v[116:117], v[128:129], v[124:125]
	v_pk_add_f32 v[118:119], v[120:121], v[122:123]
	s_nop 0
	v_pk_add_f32 v[116:117], v[116:117], v[118:119]
	s_nop 0
	v_add_f32_e32 v116, v116, v117
	v_fmamk_f32 v116, v116, 0x3a800000, v176
	v_cmp_gt_f32_e32 vcc, s11, v116
	v_mul_f32_e32 v117, 0x4b800000, v116
	s_nop 0
	v_cndmask_b32_e32 v116, v116, v117, vcc
	v_rsq_f32_e32 v116, v116
	s_nop 0
	v_mul_f32_e32 v117, 0x45800000, v116
	v_cndmask_b32_e32 v116, v116, v117, vcc
	v_mul_f32_e32 v116, 0x3db8aa3b, v116
	v_pk_mul_f32 v[112:113], v[112:113], v[116:117] op_sel_hi:[1,0]
	v_pk_mul_f32 v[110:111], v[110:111], v[116:117] op_sel_hi:[1,0]
	v_pk_mul_f32 v[118:119], v[108:109], v[116:117] op_sel_hi:[1,0]
	v_pk_mul_f32 v[108:109], v[106:107], v[116:117] op_sel_hi:[1,0]
	v_cvt_pk_bf16_f32 v106, v110, v111
	v_cvt_pk_bf16_f32 v107, v112, v113
	v_pk_mul_f32 v[104:105], v[104:105], v[116:117] op_sel_hi:[1,0]
	v_cvt_pk_bf16_f32 v108, v108, v109
	v_cvt_pk_bf16_f32 v109, v118, v119
	global_store_dwordx4 v[114:115], v[106:109], off
	v_pk_mul_f32 v[102:103], v[102:103], v[116:117] op_sel_hi:[1,0]
	s_nop 0
	v_pk_mul_f32 v[106:107], v[100:101], v[116:117] op_sel_hi:[1,0]
	v_pk_mul_f32 v[100:101], v[98:99], v[116:117] op_sel_hi:[1,0]
	v_cvt_pk_bf16_f32 v98, v102, v103
	v_cvt_pk_bf16_f32 v99, v104, v105
	s_nop 0
	v_cvt_pk_bf16_f32 v100, v100, v101
	v_cvt_pk_bf16_f32 v101, v106, v107
	global_store_dwordx4 v[114:115], v[98:101], off offset:256
	s_nop 1
	v_or_b32_e32 v100, 32, v148
	v_ashrrev_i32_e32 v101, 31, v100
	v_lshlrev_b64 v[98:99], 11, v[100:101]
	v_lshlrev_b64 v[100:101], 6, v[100:101]
	v_lshl_add_u64 v[112:113], s[2:3], 0, v[100:101]
	global_load_dwordx4 v[100:103], v[112:113], off offset:48
	global_load_dwordx4 v[104:107], v[112:113], off offset:32
	global_load_dwordx4 v[108:111], v[112:113], off offset:16
	s_nop 0
	global_load_dwordx4 v[112:115], v[112:113], off
	v_lshl_add_u64 v[98:99], s[80:81], 0, v[98:99]
	v_lshl_add_u64 v[98:99], v[98:99], 0, s[54:55]
	v_lshl_add_u64 v[98:99], v[98:99], 0, s[76:77]
	v_lshl_add_u64 v[98:99], v[98:99], 0, v[146:147]
	s_waitcnt vmcnt(2)
	v_add_f32_e32 v104, v104, v105
	v_add_f32_e32 v106, v106, v107
	s_waitcnt vmcnt(0)
	v_mov_b32_e32 v116, v113
	v_mov_b32_e32 v117, v114
	v_mov_b32_e32 v113, v115
	v_mov_b32_e32 v114, v109
	v_mov_b32_e32 v115, v110
	v_mov_b32_e32 v109, v111
	v_pk_add_f32 v[112:113], v[116:117], v[112:113]
	v_pk_add_f32 v[108:109], v[114:115], v[108:109]
	v_pk_add_f32 v[112:113], v[112:113], v[112:113] op_sel:[0,1] op_sel_hi:[1,0]
	v_pk_add_f32 v[108:109], v[108:109], v[108:109] op_sel:[0,1] op_sel_hi:[1,0]
	v_mov_b32_e32 v113, v100
	v_mov_b32_e32 v109, v101
	v_mov_b32_e32 v105, v102
	v_mov_b32_e32 v107, v103
	v_pk_add_f32 v[100:101], v[112:113], v[108:109]
	v_pk_add_f32 v[102:103], v[104:105], v[106:107]
	s_nop 0
	v_pk_add_f32 v[100:101], v[100:101], v[102:103]
	s_nop 0
	v_add_f32_e32 v100, v100, v101
	v_fmamk_f32 v100, v100, 0x3a800000, v176
	v_cmp_gt_f32_e32 vcc, s11, v100
	v_mul_f32_e32 v101, 0x4b800000, v100
	s_nop 0
	v_cndmask_b32_e32 v100, v100, v101, vcc
	v_rsq_f32_e32 v100, v100
	s_nop 0
	v_mul_f32_e32 v101, 0x45800000, v100
	v_cndmask_b32_e32 v100, v100, v101, vcc
	v_mul_f32_e32 v100, 0x3db8aa3b, v100
	v_pk_mul_f32 v[96:97], v[96:97], v[100:101] op_sel_hi:[1,0]
	v_pk_mul_f32 v[94:95], v[94:95], v[100:101] op_sel_hi:[1,0]
	v_pk_mul_f32 v[102:103], v[92:93], v[100:101] op_sel_hi:[1,0]
	v_pk_mul_f32 v[92:93], v[90:91], v[100:101] op_sel_hi:[1,0]
	v_cvt_pk_bf16_f32 v90, v94, v95
	v_cvt_pk_bf16_f32 v91, v96, v97
	v_pk_mul_f32 v[88:89], v[88:89], v[100:101] op_sel_hi:[1,0]
	v_cvt_pk_bf16_f32 v92, v92, v93
	v_cvt_pk_bf16_f32 v93, v102, v103
	global_store_dwordx4 v[98:99], v[90:93], off
	v_pk_mul_f32 v[86:87], v[86:87], v[100:101] op_sel_hi:[1,0]
	s_nop 0
	v_pk_mul_f32 v[90:91], v[84:85], v[100:101] op_sel_hi:[1,0]
	v_pk_mul_f32 v[84:85], v[82:83], v[100:101] op_sel_hi:[1,0]
	v_cvt_pk_bf16_f32 v82, v86, v87
	v_cvt_pk_bf16_f32 v83, v88, v89
	s_nop 0
	v_cvt_pk_bf16_f32 v84, v84, v85
	v_cvt_pk_bf16_f32 v85, v90, v91
	global_store_dwordx4 v[98:99], v[82:85], off offset:256
	s_nop 1
	v_or_b32_e32 v84, 48, v148
	v_ashrrev_i32_e32 v85, 31, v84
	v_lshlrev_b64 v[82:83], 11, v[84:85]
	v_lshlrev_b64 v[84:85], 6, v[84:85]
	v_lshl_add_u64 v[96:97], s[2:3], 0, v[84:85]
	global_load_dwordx4 v[84:87], v[96:97], off offset:48
	global_load_dwordx4 v[88:91], v[96:97], off offset:32
	global_load_dwordx4 v[92:95], v[96:97], off offset:16
	s_nop 0
	global_load_dwordx4 v[96:99], v[96:97], off
	v_lshl_add_u64 v[82:83], s[80:81], 0, v[82:83]
	v_lshl_add_u64 v[82:83], v[82:83], 0, s[54:55]
	v_lshl_add_u64 v[82:83], v[82:83], 0, s[76:77]
	v_lshl_add_u64 v[82:83], v[82:83], 0, v[146:147]
	s_waitcnt vmcnt(2)
	v_add_f32_e32 v88, v88, v89
	v_add_f32_e32 v90, v90, v91
	s_waitcnt vmcnt(0)
	v_mov_b32_e32 v100, v97
	v_mov_b32_e32 v101, v98
	v_mov_b32_e32 v97, v99
	v_mov_b32_e32 v98, v93
	v_mov_b32_e32 v99, v94
	v_mov_b32_e32 v93, v95
	v_pk_add_f32 v[96:97], v[100:101], v[96:97]
	v_pk_add_f32 v[92:93], v[98:99], v[92:93]
	v_pk_add_f32 v[96:97], v[96:97], v[96:97] op_sel:[0,1] op_sel_hi:[1,0]
	v_pk_add_f32 v[92:93], v[92:93], v[92:93] op_sel:[0,1] op_sel_hi:[1,0]
	v_mov_b32_e32 v97, v84
	v_mov_b32_e32 v93, v85
	v_mov_b32_e32 v89, v86
	v_mov_b32_e32 v91, v87
	v_pk_add_f32 v[84:85], v[96:97], v[92:93]
	v_pk_add_f32 v[86:87], v[88:89], v[90:91]
	s_nop 0
	v_pk_add_f32 v[84:85], v[84:85], v[86:87]
	s_nop 0
	v_add_f32_e32 v84, v84, v85
	v_fmamk_f32 v84, v84, 0x3a800000, v176
	v_cmp_gt_f32_e32 vcc, s11, v84
	v_mul_f32_e32 v85, 0x4b800000, v84
	s_nop 0
	v_cndmask_b32_e32 v84, v84, v85, vcc
	v_rsq_f32_e32 v84, v84
	s_nop 0
	v_mul_f32_e32 v85, 0x45800000, v84
	v_cndmask_b32_e32 v84, v84, v85, vcc
	v_mul_f32_e32 v84, 0x3db8aa3b, v84
	v_pk_mul_f32 v[80:81], v[80:81], v[84:85] op_sel_hi:[1,0]
	v_pk_mul_f32 v[78:79], v[78:79], v[84:85] op_sel_hi:[1,0]
	v_pk_mul_f32 v[86:87], v[76:77], v[84:85] op_sel_hi:[1,0]
	v_pk_mul_f32 v[76:77], v[74:75], v[84:85] op_sel_hi:[1,0]
	v_cvt_pk_bf16_f32 v74, v78, v79
	v_cvt_pk_bf16_f32 v75, v80, v81
	v_pk_mul_f32 v[72:73], v[72:73], v[84:85] op_sel_hi:[1,0]
	v_cvt_pk_bf16_f32 v76, v76, v77
	v_cvt_pk_bf16_f32 v77, v86, v87
	global_store_dwordx4 v[82:83], v[74:77], off
	v_pk_mul_f32 v[70:71], v[70:71], v[84:85] op_sel_hi:[1,0]
	s_nop 0
	v_pk_mul_f32 v[74:75], v[68:69], v[84:85] op_sel_hi:[1,0]
	v_pk_mul_f32 v[68:69], v[66:67], v[84:85] op_sel_hi:[1,0]
	v_cvt_pk_bf16_f32 v66, v70, v71
	v_cvt_pk_bf16_f32 v67, v72, v73
	s_nop 0
	v_cvt_pk_bf16_f32 v68, v68, v69
	v_cvt_pk_bf16_f32 v69, v74, v75
	global_store_dwordx4 v[82:83], v[66:69], off offset:256
	s_nop 1
	v_add_u32_e32 v68, 0x80, v148
	v_ashrrev_i32_e32 v69, 31, v68
	v_lshlrev_b64 v[66:67], 11, v[68:69]
	v_lshlrev_b64 v[68:69], 6, v[68:69]
	v_lshl_add_u64 v[80:81], s[2:3], 0, v[68:69]
	global_load_dwordx4 v[68:71], v[80:81], off offset:48
	global_load_dwordx4 v[72:75], v[80:81], off offset:32
	global_load_dwordx4 v[76:79], v[80:81], off offset:16
	s_nop 0
	global_load_dwordx4 v[80:83], v[80:81], off
	v_lshl_add_u64 v[66:67], s[80:81], 0, v[66:67]
	v_lshl_add_u64 v[66:67], v[66:67], 0, s[54:55]
	v_lshl_add_u64 v[66:67], v[66:67], 0, s[76:77]
	v_lshl_add_u64 v[66:67], v[66:67], 0, v[146:147]
	s_waitcnt vmcnt(2)
	v_add_f32_e32 v72, v72, v73
	v_add_f32_e32 v74, v74, v75
	s_waitcnt vmcnt(0)
	v_mov_b32_e32 v84, v81
	v_mov_b32_e32 v85, v82
	v_mov_b32_e32 v81, v83
	v_mov_b32_e32 v82, v77
	v_mov_b32_e32 v83, v78
	v_mov_b32_e32 v77, v79
	v_pk_add_f32 v[80:81], v[84:85], v[80:81]
	v_pk_add_f32 v[76:77], v[82:83], v[76:77]
	v_pk_add_f32 v[80:81], v[80:81], v[80:81] op_sel:[0,1] op_sel_hi:[1,0]
	v_pk_add_f32 v[76:77], v[76:77], v[76:77] op_sel:[0,1] op_sel_hi:[1,0]
	v_mov_b32_e32 v81, v68
	v_mov_b32_e32 v77, v69
	v_mov_b32_e32 v73, v70
	v_mov_b32_e32 v75, v71
	v_pk_add_f32 v[68:69], v[80:81], v[76:77]
	v_pk_add_f32 v[70:71], v[72:73], v[74:75]
	s_nop 0
	v_pk_add_f32 v[68:69], v[68:69], v[70:71]
	s_nop 0
	v_add_f32_e32 v68, v68, v69
	v_fmamk_f32 v68, v68, 0x3a800000, v176
	v_cmp_gt_f32_e32 vcc, s11, v68
	v_mul_f32_e32 v69, 0x4b800000, v68
	s_nop 0
	v_cndmask_b32_e32 v68, v68, v69, vcc
	v_rsq_f32_e32 v68, v68
	s_nop 0
	v_mul_f32_e32 v69, 0x45800000, v68
	v_cndmask_b32_e32 v68, v68, v69, vcc
	v_mul_f32_e32 v68, 0x3db8aa3b, v68
	v_pk_mul_f32 v[62:63], v[62:63], v[68:69] op_sel_hi:[1,0]
	v_pk_mul_f32 v[60:61], v[60:61], v[68:69] op_sel_hi:[1,0]
	v_pk_mul_f32 v[70:71], v[58:59], v[68:69] op_sel_hi:[1,0]
	v_pk_mul_f32 v[58:59], v[56:57], v[68:69] op_sel_hi:[1,0]
	v_cvt_pk_bf16_f32 v56, v60, v61
	v_cvt_pk_bf16_f32 v57, v62, v63
	v_pk_mul_f32 v[54:55], v[54:55], v[68:69] op_sel_hi:[1,0]
	v_cvt_pk_bf16_f32 v58, v58, v59
	v_cvt_pk_bf16_f32 v59, v70, v71
	global_store_dwordx4 v[66:67], v[56:59], off
	v_pk_mul_f32 v[52:53], v[52:53], v[68:69] op_sel_hi:[1,0]
	s_nop 0
	v_pk_mul_f32 v[56:57], v[50:51], v[68:69] op_sel_hi:[1,0]
	v_pk_mul_f32 v[50:51], v[48:49], v[68:69] op_sel_hi:[1,0]
	v_cvt_pk_bf16_f32 v48, v52, v53
	v_cvt_pk_bf16_f32 v49, v54, v55
	s_nop 0
	v_cvt_pk_bf16_f32 v50, v50, v51
	v_cvt_pk_bf16_f32 v51, v56, v57
	global_store_dwordx4 v[66:67], v[48:51], off offset:256
	s_nop 1
	v_add_u32_e32 v50, 0x90, v148
	v_ashrrev_i32_e32 v51, 31, v50
	v_lshlrev_b64 v[48:49], 11, v[50:51]
	v_lshlrev_b64 v[50:51], 6, v[50:51]
	v_lshl_add_u64 v[62:63], s[2:3], 0, v[50:51]
	global_load_dwordx4 v[50:53], v[62:63], off offset:48
	global_load_dwordx4 v[54:57], v[62:63], off offset:32
	global_load_dwordx4 v[58:61], v[62:63], off offset:16
	global_load_dwordx4 v[66:69], v[62:63], off
	v_lshl_add_u64 v[48:49], s[80:81], 0, v[48:49]
	v_lshl_add_u64 v[48:49], v[48:49], 0, s[54:55]
	v_lshl_add_u64 v[48:49], v[48:49], 0, s[76:77]
	v_lshl_add_u64 v[48:49], v[48:49], 0, v[146:147]
	s_waitcnt vmcnt(2)
	v_add_f32_e32 v54, v54, v55
	v_add_f32_e32 v56, v56, v57
	s_waitcnt vmcnt(0)
	v_mov_b32_e32 v62, v67
	v_mov_b32_e32 v63, v68
	v_mov_b32_e32 v67, v69
	v_pk_add_f32 v[62:63], v[62:63], v[66:67]
	v_mov_b32_e32 v66, v59
	v_mov_b32_e32 v67, v60
	v_mov_b32_e32 v59, v61
	v_pk_add_f32 v[58:59], v[66:67], v[58:59]
	v_pk_add_f32 v[62:63], v[62:63], v[62:63] op_sel:[0,1] op_sel_hi:[1,0]
	v_pk_add_f32 v[58:59], v[58:59], v[58:59] op_sel:[0,1] op_sel_hi:[1,0]
	v_mov_b32_e32 v63, v50
	v_mov_b32_e32 v59, v51
	v_mov_b32_e32 v55, v52
	v_mov_b32_e32 v57, v53
	v_pk_add_f32 v[50:51], v[62:63], v[58:59]
	v_pk_add_f32 v[52:53], v[54:55], v[56:57]
	s_nop 0
	v_pk_add_f32 v[50:51], v[50:51], v[52:53]
	s_nop 0
	v_add_f32_e32 v50, v50, v51
	v_fmamk_f32 v50, v50, 0x3a800000, v176
	v_cmp_gt_f32_e32 vcc, s11, v50
	v_mul_f32_e32 v51, 0x4b800000, v50
	s_nop 0
	v_cndmask_b32_e32 v50, v50, v51, vcc
	v_rsq_f32_e32 v50, v50
	s_nop 0
	v_mul_f32_e32 v51, 0x45800000, v50
	v_cndmask_b32_e32 v50, v50, v51, vcc
	v_mul_f32_e32 v50, 0x3db8aa3b, v50
	v_pk_mul_f32 v[46:47], v[46:47], v[50:51] op_sel_hi:[1,0]
	v_pk_mul_f32 v[44:45], v[44:45], v[50:51] op_sel_hi:[1,0]
	v_pk_mul_f32 v[52:53], v[42:43], v[50:51] op_sel_hi:[1,0]
	v_pk_mul_f32 v[42:43], v[40:41], v[50:51] op_sel_hi:[1,0]
	v_cvt_pk_bf16_f32 v40, v44, v45
	v_cvt_pk_bf16_f32 v41, v46, v47
	v_pk_mul_f32 v[38:39], v[38:39], v[50:51] op_sel_hi:[1,0]
	v_cvt_pk_bf16_f32 v42, v42, v43
	v_cvt_pk_bf16_f32 v43, v52, v53
	global_store_dwordx4 v[48:49], v[40:43], off
	v_pk_mul_f32 v[36:37], v[36:37], v[50:51] op_sel_hi:[1,0]
	s_nop 0
	v_pk_mul_f32 v[40:41], v[34:35], v[50:51] op_sel_hi:[1,0]
	v_pk_mul_f32 v[34:35], v[32:33], v[50:51] op_sel_hi:[1,0]
	v_cvt_pk_bf16_f32 v32, v36, v37
	v_cvt_pk_bf16_f32 v33, v38, v39
	s_nop 0
	v_cvt_pk_bf16_f32 v34, v34, v35
	v_cvt_pk_bf16_f32 v35, v40, v41
	global_store_dwordx4 v[48:49], v[32:35], off offset:256
	s_nop 1
	v_add_u32_e32 v34, 0xa0, v148
	v_ashrrev_i32_e32 v35, 31, v34
	v_lshlrev_b64 v[32:33], 11, v[34:35]
	v_lshlrev_b64 v[34:35], 6, v[34:35]
	v_lshl_add_u64 v[46:47], s[2:3], 0, v[34:35]
	global_load_dwordx4 v[34:37], v[46:47], off offset:48
	global_load_dwordx4 v[38:41], v[46:47], off offset:32
	global_load_dwordx4 v[42:45], v[46:47], off offset:16
	s_nop 0
	global_load_dwordx4 v[46:49], v[46:47], off
	v_lshl_add_u64 v[32:33], s[80:81], 0, v[32:33]
	v_lshl_add_u64 v[32:33], v[32:33], 0, s[54:55]
	v_lshl_add_u64 v[32:33], v[32:33], 0, s[76:77]
	v_lshl_add_u64 v[32:33], v[32:33], 0, v[146:147]
	s_waitcnt vmcnt(2)
	v_add_f32_e32 v38, v38, v39
	v_add_f32_e32 v40, v40, v41
	s_waitcnt vmcnt(0)
	v_mov_b32_e32 v50, v47
	v_mov_b32_e32 v51, v48
	v_mov_b32_e32 v47, v49
	v_mov_b32_e32 v48, v43
	v_mov_b32_e32 v49, v44
	v_mov_b32_e32 v43, v45
	v_pk_add_f32 v[46:47], v[50:51], v[46:47]
	v_pk_add_f32 v[42:43], v[48:49], v[42:43]
	v_pk_add_f32 v[46:47], v[46:47], v[46:47] op_sel:[0,1] op_sel_hi:[1,0]
	v_pk_add_f32 v[42:43], v[42:43], v[42:43] op_sel:[0,1] op_sel_hi:[1,0]
	v_mov_b32_e32 v47, v34
	v_mov_b32_e32 v43, v35
	v_mov_b32_e32 v39, v36
	v_mov_b32_e32 v41, v37
	v_pk_add_f32 v[34:35], v[46:47], v[42:43]
	v_pk_add_f32 v[36:37], v[38:39], v[40:41]
	s_nop 0
	v_pk_add_f32 v[34:35], v[34:35], v[36:37]
	s_nop 0
	v_add_f32_e32 v34, v34, v35
	v_fmamk_f32 v34, v34, 0x3a800000, v176
	v_cmp_gt_f32_e32 vcc, s11, v34
	v_mul_f32_e32 v35, 0x4b800000, v34
	s_nop 0
	v_cndmask_b32_e32 v34, v34, v35, vcc
	v_rsq_f32_e32 v34, v34
	s_nop 0
	v_mul_f32_e32 v35, 0x45800000, v34
	v_cndmask_b32_e32 v34, v34, v35, vcc
	v_mul_f32_e32 v34, 0x3db8aa3b, v34
	v_pk_mul_f32 v[30:31], v[30:31], v[34:35] op_sel_hi:[1,0]
	v_pk_mul_f32 v[28:29], v[28:29], v[34:35] op_sel_hi:[1,0]
	v_pk_mul_f32 v[36:37], v[26:27], v[34:35] op_sel_hi:[1,0]
	v_pk_mul_f32 v[26:27], v[24:25], v[34:35] op_sel_hi:[1,0]
	v_cvt_pk_bf16_f32 v24, v28, v29
	v_cvt_pk_bf16_f32 v25, v30, v31
	v_pk_mul_f32 v[22:23], v[22:23], v[34:35] op_sel_hi:[1,0]
	v_cvt_pk_bf16_f32 v26, v26, v27
	v_cvt_pk_bf16_f32 v27, v36, v37
	global_store_dwordx4 v[32:33], v[24:27], off
	v_pk_mul_f32 v[20:21], v[20:21], v[34:35] op_sel_hi:[1,0]
	s_nop 0
	v_pk_mul_f32 v[24:25], v[18:19], v[34:35] op_sel_hi:[1,0]
	v_pk_mul_f32 v[18:19], v[16:17], v[34:35] op_sel_hi:[1,0]
	v_cvt_pk_bf16_f32 v16, v20, v21
	v_cvt_pk_bf16_f32 v17, v22, v23
	s_nop 0
	v_cvt_pk_bf16_f32 v18, v18, v19
	v_cvt_pk_bf16_f32 v19, v24, v25
	global_store_dwordx4 v[32:33], v[16:19], off offset:256
	s_nop 1
	v_add_u32_e32 v18, 0xb0, v148
	v_ashrrev_i32_e32 v19, 31, v18
	v_lshlrev_b64 v[16:17], 11, v[18:19]
	v_lshlrev_b64 v[18:19], 6, v[18:19]
	v_lshl_add_u64 v[30:31], s[2:3], 0, v[18:19]
	global_load_dwordx4 v[18:21], v[30:31], off offset:48
	global_load_dwordx4 v[22:25], v[30:31], off offset:32
	global_load_dwordx4 v[26:29], v[30:31], off offset:16
	s_nop 0
	global_load_dwordx4 v[30:33], v[30:31], off
	v_lshl_add_u64 v[16:17], s[80:81], 0, v[16:17]
	v_lshl_add_u64 v[16:17], v[16:17], 0, s[54:55]
	v_lshl_add_u64 v[16:17], v[16:17], 0, s[76:77]
	v_lshl_add_u64 v[16:17], v[16:17], 0, v[146:147]
	s_waitcnt vmcnt(2)
	v_add_f32_e32 v22, v22, v23
	v_add_f32_e32 v24, v24, v25
	s_waitcnt vmcnt(0)
	v_mov_b32_e32 v34, v31
	v_mov_b32_e32 v35, v32
	v_mov_b32_e32 v31, v33
	v_mov_b32_e32 v32, v27
	v_mov_b32_e32 v33, v28
	v_mov_b32_e32 v27, v29
	v_pk_add_f32 v[30:31], v[34:35], v[30:31]
	v_pk_add_f32 v[26:27], v[32:33], v[26:27]
	v_pk_add_f32 v[30:31], v[30:31], v[30:31] op_sel:[0,1] op_sel_hi:[1,0]
	v_pk_add_f32 v[26:27], v[26:27], v[26:27] op_sel:[0,1] op_sel_hi:[1,0]
	v_mov_b32_e32 v31, v18
	v_mov_b32_e32 v27, v19
	v_mov_b32_e32 v23, v20
	v_mov_b32_e32 v25, v21
	v_pk_add_f32 v[18:19], v[30:31], v[26:27]
	v_pk_add_f32 v[20:21], v[22:23], v[24:25]
	s_nop 0
	v_pk_add_f32 v[18:19], v[18:19], v[20:21]
	s_nop 0
	v_add_f32_e32 v18, v18, v19
	v_fmamk_f32 v18, v18, 0x3a800000, v176
	v_cmp_gt_f32_e32 vcc, s11, v18
	v_mul_f32_e32 v19, 0x4b800000, v18
	s_nop 0
	v_cndmask_b32_e32 v18, v18, v19, vcc
	v_rsq_f32_e32 v18, v18
	s_nop 0
	v_mul_f32_e32 v19, 0x45800000, v18
	v_cndmask_b32_e32 v18, v18, v19, vcc
	v_mul_f32_e32 v18, 0x3db8aa3b, v18
	v_pk_mul_f32 v[14:15], v[14:15], v[18:19] op_sel_hi:[1,0]
	v_pk_mul_f32 v[12:13], v[12:13], v[18:19] op_sel_hi:[1,0]
	v_pk_mul_f32 v[20:21], v[10:11], v[18:19] op_sel_hi:[1,0]
	v_pk_mul_f32 v[10:11], v[8:9], v[18:19] op_sel_hi:[1,0]
	v_cvt_pk_bf16_f32 v8, v12, v13
	v_cvt_pk_bf16_f32 v9, v14, v15
	s_andn2_b64 vcc, exec, s[38:39]
	v_cvt_pk_bf16_f32 v10, v10, v11
	v_cvt_pk_bf16_f32 v11, v20, v21
	global_store_dwordx4 v[16:17], v[8:11], off
	v_pk_mul_f32 v[6:7], v[6:7], v[18:19] op_sel_hi:[1,0]
	v_pk_mul_f32 v[4:5], v[4:5], v[18:19] op_sel_hi:[1,0]
	v_pk_mul_f32 v[8:9], v[2:3], v[18:19] op_sel_hi:[1,0]
	v_pk_mul_f32 v[2:3], v[0:1], v[18:19] op_sel_hi:[1,0]
	v_cvt_pk_bf16_f32 v0, v4, v5
	v_cvt_pk_bf16_f32 v1, v6, v7
	s_nop 0
	v_cvt_pk_bf16_f32 v2, v2, v3
	v_cvt_pk_bf16_f32 v3, v8, v9
	global_store_dwordx4 v[16:17], v[0:3], off offset:256
.Lxq_done:
	s_cbranch_vccnz .LBB0_58
	s_andn2_b64 vcc, exec, s[0:1]
	s_cbranch_vccnz .LBB0_57
	s_barrier
	s_branch .LBB0_57
